# combo9 + K-loop LDS-DMA rebalance: last piece of the first K-tile's L2 segment issued at the head of the next L1 segment (2/5/3/6 pieces per segment, issue order unchanged, that wait vmcnt(7))
# speedup vs baseline: 1.0080x; 1.0080x over previous
.LBB0_324:
	s_add_i32 vcc_lo, s66, 2
	s_add_u32 s34, s8, 0xfff00080
	s_addc_u32 s35, s9, -1
	s_add_i32 s89, 0, 0x10000
	s_cmp_eq_u32 s59, s66
	s_cselect_b32 s95, s65, s35
	s_cselect_b32 s94, s64, s34
	v_add_u32_e32 v0, s89, v217
	s_cselect_b32 s67, s53, s80
	s_cselect_b32 s66, s52, s70
	s_add_i32 vcc_hi, 0, 0x14000
	ds_read_b128 v[132:135], v0
	ds_read_b128 v[136:139], v0 offset:1024
	ds_read_b128 v[140:143], v0 offset:2048
	ds_read_b128 v[144:147], v0 offset:3072
	v_add_u32_e32 v0, vcc_hi, v217
	ds_read_b128 v[148:151], v0
	ds_read_b128 v[152:155], v0 offset:1024
	ds_read_b128 v[156:159], v0 offset:2048
	ds_read_b128 v[160:163], v0 offset:3072
	v_add_u32_e32 v0, 0, v216
	s_add_i32 m0, s29, 0xc000
	ds_read_b128 v[164:167], v0
	ds_read_b128 v[168:171], v0 offset:1024
	ds_read_b128 v[172:175], v0 offset:2048
	ds_read_b128 v[176:179], v0 offset:3072
	ds_read_b128 v[180:183], v0 offset:4096
	ds_read_b128 v[184:187], v0 offset:5120
	ds_read_b128 v[188:191], v0 offset:6144
	ds_read_b128 v[250:253], v0 offset:7168
	global_load_lds_dwordx4 v204, s[8:9]
	s_add_i32 m0, s29, 0xe000
	s_nop 0
	global_load_lds_dwordx4 v206, s[8:9]
	s_waitcnt vmcnt(8) lgkmcnt(0)
	s_barrier
	v_mfma_f32_16x16x32_bf16 v[128:131], v[132:135], v[164:167], v[128:131]
	v_mfma_f32_16x16x32_bf16 v[112:115], v[140:143], v[164:167], v[112:115]
	v_mfma_f32_16x16x32_bf16 v[120:123], v[132:135], v[172:175], v[120:123]
	v_mfma_f32_16x16x32_bf16 v[96:99], v[140:143], v[172:175], v[96:99]
	v_mfma_f32_16x16x32_bf16 v[104:107], v[132:135], v[180:183], v[104:107]
	v_mfma_f32_16x16x32_bf16 v[88:91], v[140:143], v[180:183], v[88:91]
	v_mfma_f32_16x16x32_bf16 v[84:87], v[132:135], v[188:191], v[84:87]
	v_mfma_f32_16x16x32_bf16 v[72:75], v[140:143], v[188:191], v[72:75]
	v_mfma_f32_16x16x32_bf16 v[128:131], v[136:139], v[168:171], v[128:131]
	v_mfma_f32_16x16x32_bf16 v[112:115], v[144:147], v[168:171], v[112:115]
	v_mfma_f32_16x16x32_bf16 v[120:123], v[136:139], v[176:179], v[120:123]
	v_mfma_f32_16x16x32_bf16 v[96:99], v[144:147], v[176:179], v[96:99]
	v_mfma_f32_16x16x32_bf16 v[104:107], v[136:139], v[184:187], v[104:107]
	v_mfma_f32_16x16x32_bf16 v[88:91], v[144:147], v[184:187], v[88:91]
	v_mfma_f32_16x16x32_bf16 v[84:87], v[136:139], v[250:253], v[84:87]
	v_mfma_f32_16x16x32_bf16 v[72:75], v[144:147], v[250:253], v[72:75]
	v_mfma_f32_16x16x32_bf16 v[124:127], v[148:151], v[164:167], v[124:127]
	v_mfma_f32_16x16x32_bf16 v[108:111], v[156:159], v[164:167], v[108:111]
	v_mfma_f32_16x16x32_bf16 v[116:119], v[148:151], v[172:175], v[116:119]
	v_mfma_f32_16x16x32_bf16 v[92:95], v[156:159], v[172:175], v[92:95]
	v_mfma_f32_16x16x32_bf16 v[100:103], v[148:151], v[180:183], v[100:103]
	v_mfma_f32_16x16x32_bf16 v[80:83], v[156:159], v[180:183], v[80:83]
	v_mfma_f32_16x16x32_bf16 v[76:79], v[148:151], v[188:191], v[76:79]
	v_mfma_f32_16x16x32_bf16 v[68:71], v[156:159], v[188:191], v[68:71]
	v_mfma_f32_16x16x32_bf16 v[124:127], v[152:155], v[168:171], v[124:127]
	v_mfma_f32_16x16x32_bf16 v[108:111], v[160:163], v[168:171], v[108:111]
	v_mfma_f32_16x16x32_bf16 v[116:119], v[152:155], v[176:179], v[116:119]
	v_mfma_f32_16x16x32_bf16 v[92:95], v[160:163], v[176:179], v[92:95]
	v_mfma_f32_16x16x32_bf16 v[100:103], v[152:155], v[184:187], v[100:103]
	v_mfma_f32_16x16x32_bf16 v[80:83], v[160:163], v[184:187], v[80:83]
	v_mfma_f32_16x16x32_bf16 v[76:79], v[152:155], v[250:253], v[76:79]
	v_mfma_f32_16x16x32_bf16 v[68:71], v[160:163], v[250:253], v[68:71]
	s_barrier
	s_add_i32 s34, s89, s0
	s_mov_b32 m0, s34
	ds_read_b128 v[164:167], v0 offset:16384
	ds_read_b128 v[168:171], v0 offset:17408
	ds_read_b128 v[172:175], v0 offset:18432
	ds_read_b128 v[176:179], v0 offset:19456
	ds_read_b128 v[180:183], v0 offset:20480
	ds_read_b128 v[184:187], v0 offset:21504
	ds_read_b128 v[188:191], v0 offset:22528
	ds_read_b128 v[250:253], v0 offset:23552
	global_load_lds_dwordx4 v196, s[66:67]
	s_add_i32 m0, s34, 0x2000
	s_add_u32 s34, s66, 0x4000
	s_addc_u32 s35, s67, 0
	s_add_i32 s89, vcc_hi, s0
	global_load_lds_dwordx4 v200, s[66:67]
	s_mov_b32 m0, s89
	s_nop 0
	global_load_lds_dwordx4 v196, s[34:35]
	s_add_i32 m0, s89, 0x2000
	s_nop 0
	global_load_lds_dwordx4 v200, s[34:35]
	s_mov_b32 m0, s29
	s_nop 0
	global_load_lds_dwordx4 v198, s[94:95]
	s_waitcnt vmcnt(7) lgkmcnt(0)
	s_barrier
	v_mfma_f32_16x16x32_bf16 v[64:67], v[132:135], v[164:167], v[64:67]
	v_mfma_f32_16x16x32_bf16 v[56:59], v[140:143], v[164:167], v[56:59]
	v_mfma_f32_16x16x32_bf16 v[48:51], v[132:135], v[172:175], v[48:51]
	v_mfma_f32_16x16x32_bf16 v[40:43], v[140:143], v[172:175], v[40:43]
	v_mfma_f32_16x16x32_bf16 v[30:33], v[132:135], v[180:183], v[30:33]
	v_mfma_f32_16x16x32_bf16 v[26:29], v[140:143], v[180:183], v[26:29]
	v_mfma_f32_16x16x32_bf16 v[14:17], v[132:135], v[188:191], v[14:17]
	v_mfma_f32_16x16x32_bf16 v[10:13], v[140:143], v[188:191], v[10:13]
	v_mfma_f32_16x16x32_bf16 v[64:67], v[136:139], v[168:171], v[64:67]
	v_mfma_f32_16x16x32_bf16 v[56:59], v[144:147], v[168:171], v[56:59]
	v_mfma_f32_16x16x32_bf16 v[48:51], v[136:139], v[176:179], v[48:51]
	v_mfma_f32_16x16x32_bf16 v[40:43], v[144:147], v[176:179], v[40:43]
	v_mfma_f32_16x16x32_bf16 v[30:33], v[136:139], v[184:187], v[30:33]
	v_mfma_f32_16x16x32_bf16 v[26:29], v[144:147], v[184:187], v[26:29]
	v_mfma_f32_16x16x32_bf16 v[14:17], v[136:139], v[250:253], v[14:17]
	v_mfma_f32_16x16x32_bf16 v[10:13], v[144:147], v[250:253], v[10:13]
	v_mfma_f32_16x16x32_bf16 v[60:63], v[148:151], v[164:167], v[60:63]
	v_mfma_f32_16x16x32_bf16 v[52:55], v[156:159], v[164:167], v[52:55]
	v_mfma_f32_16x16x32_bf16 v[44:47], v[148:151], v[172:175], v[44:47]
	v_mfma_f32_16x16x32_bf16 v[36:39], v[156:159], v[172:175], v[36:39]
	v_mfma_f32_16x16x32_bf16 v[22:25], v[148:151], v[180:183], v[22:25]
	v_mfma_f32_16x16x32_bf16 v[18:21], v[156:159], v[180:183], v[18:21]
	v_mfma_f32_16x16x32_bf16 v[6:9], v[148:151], v[188:191], v[6:9]
	v_mfma_f32_16x16x32_bf16 v[2:5], v[156:159], v[188:191], v[2:5]
	v_mfma_f32_16x16x32_bf16 v[60:63], v[152:155], v[168:171], v[60:63]
	v_mfma_f32_16x16x32_bf16 v[52:55], v[160:163], v[168:171], v[52:55]
	v_mfma_f32_16x16x32_bf16 v[44:47], v[152:155], v[176:179], v[44:47]
	v_mfma_f32_16x16x32_bf16 v[36:39], v[160:163], v[176:179], v[36:39]
	v_mfma_f32_16x16x32_bf16 v[22:25], v[152:155], v[184:187], v[22:25]
	v_mfma_f32_16x16x32_bf16 v[18:21], v[160:163], v[184:187], v[18:21]
	v_mfma_f32_16x16x32_bf16 v[6:9], v[152:155], v[250:253], v[6:9]
	v_mfma_f32_16x16x32_bf16 v[2:5], v[160:163], v[250:253], v[2:5]
	s_barrier
	s_mov_b32 m0, s45
	s_nop 0
	global_load_lds_dwordx4 v202, s[94:95]
	s_add_i32 s89, 0, 0x18000
	s_add_i32 vcc_hi, 0, 0x1c000
	v_add_u32_e32 v144, s89, v217
	v_add_u32_e32 v160, vcc_hi, v217
	ds_read_b128 v[132:135], v144
	ds_read_b128 v[136:139], v144 offset:1024
	ds_read_b128 v[140:143], v144 offset:2048
	ds_read_b128 v[144:147], v144 offset:3072
	ds_read_b128 v[148:151], v160
	ds_read_b128 v[152:155], v160 offset:1024
	ds_read_b128 v[156:159], v160 offset:2048
	ds_read_b128 v[160:163], v160 offset:3072
	s_add_u32 s34, s94, 0x100000
	s_addc_u32 s35, s95, 0
	s_mov_b32 m0, s82
	ds_read_b128 v[164:167], v0 offset:32768
	ds_read_b128 v[168:171], v0 offset:33792
	ds_read_b128 v[172:175], v0 offset:34816
	ds_read_b128 v[176:179], v0 offset:35840
	ds_read_b128 v[180:183], v0 offset:36864
	ds_read_b128 v[184:187], v0 offset:37888
	ds_read_b128 v[188:191], v0 offset:38912
	ds_read_b128 v[250:253], v0 offset:39936
	global_load_lds_dwordx4 v198, s[34:35]
	s_mov_b32 m0, s90
	s_nop 0
	global_load_lds_dwordx4 v202, s[34:35]
	s_waitcnt vmcnt(8) lgkmcnt(0)
	s_barrier
	v_mfma_f32_16x16x32_bf16 v[128:131], v[132:135], v[164:167], v[128:131]
	v_mfma_f32_16x16x32_bf16 v[112:115], v[140:143], v[164:167], v[112:115]
	v_mfma_f32_16x16x32_bf16 v[120:123], v[132:135], v[172:175], v[120:123]
	v_mfma_f32_16x16x32_bf16 v[96:99], v[140:143], v[172:175], v[96:99]
	v_mfma_f32_16x16x32_bf16 v[104:107], v[132:135], v[180:183], v[104:107]
	v_mfma_f32_16x16x32_bf16 v[88:91], v[140:143], v[180:183], v[88:91]
	v_mfma_f32_16x16x32_bf16 v[84:87], v[132:135], v[188:191], v[84:87]
	v_mfma_f32_16x16x32_bf16 v[72:75], v[140:143], v[188:191], v[72:75]
	v_mfma_f32_16x16x32_bf16 v[128:131], v[136:139], v[168:171], v[128:131]
	v_mfma_f32_16x16x32_bf16 v[112:115], v[144:147], v[168:171], v[112:115]
	v_mfma_f32_16x16x32_bf16 v[120:123], v[136:139], v[176:179], v[120:123]
	v_mfma_f32_16x16x32_bf16 v[96:99], v[144:147], v[176:179], v[96:99]
	v_mfma_f32_16x16x32_bf16 v[104:107], v[136:139], v[184:187], v[104:107]
	v_mfma_f32_16x16x32_bf16 v[88:91], v[144:147], v[184:187], v[88:91]
	v_mfma_f32_16x16x32_bf16 v[84:87], v[136:139], v[250:253], v[84:87]
	v_mfma_f32_16x16x32_bf16 v[72:75], v[144:147], v[250:253], v[72:75]
	v_mfma_f32_16x16x32_bf16 v[124:127], v[148:151], v[164:167], v[124:127]
	v_mfma_f32_16x16x32_bf16 v[108:111], v[156:159], v[164:167], v[108:111]
	v_mfma_f32_16x16x32_bf16 v[116:119], v[148:151], v[172:175], v[116:119]
	v_mfma_f32_16x16x32_bf16 v[92:95], v[156:159], v[172:175], v[92:95]
	v_mfma_f32_16x16x32_bf16 v[100:103], v[148:151], v[180:183], v[100:103]
	v_mfma_f32_16x16x32_bf16 v[80:83], v[156:159], v[180:183], v[80:83]
	v_mfma_f32_16x16x32_bf16 v[76:79], v[148:151], v[188:191], v[76:79]
	v_mfma_f32_16x16x32_bf16 v[68:71], v[156:159], v[188:191], v[68:71]
	v_mfma_f32_16x16x32_bf16 v[124:127], v[152:155], v[168:171], v[124:127]
	v_mfma_f32_16x16x32_bf16 v[108:111], v[160:163], v[168:171], v[108:111]
	v_mfma_f32_16x16x32_bf16 v[116:119], v[152:155], v[176:179], v[116:119]
	v_mfma_f32_16x16x32_bf16 v[92:95], v[160:163], v[176:179], v[92:95]
	v_mfma_f32_16x16x32_bf16 v[100:103], v[152:155], v[184:187], v[100:103]
	v_mfma_f32_16x16x32_bf16 v[80:83], v[160:163], v[184:187], v[80:83]
	v_mfma_f32_16x16x32_bf16 v[76:79], v[152:155], v[250:253], v[76:79]
	v_mfma_f32_16x16x32_bf16 v[68:71], v[160:163], v[250:253], v[68:71]
	s_barrier
	s_add_u32 s34, s66, 0x8000
	s_addc_u32 s35, s67, 0
	s_add_i32 s89, s89, s0
	s_mov_b32 m0, s89
	ds_read_b128 v[164:167], v0 offset:49152
	ds_read_b128 v[168:171], v0 offset:50176
	ds_read_b128 v[172:175], v0 offset:51200
	ds_read_b128 v[176:179], v0 offset:52224
	ds_read_b128 v[180:183], v0 offset:53248
	ds_read_b128 v[184:187], v0 offset:54272
	ds_read_b128 v[188:191], v0 offset:55296
	ds_read_b128 v[250:253], v0 offset:56320
	global_load_lds_dwordx4 v196, s[34:35]
	s_add_i32 m0, s89, 0x2000
	v_lshl_add_u64 v[210:211], s[34:35], 0, v[200:201]
	s_add_u32 s34, s66, 0xc000
	s_addc_u32 s35, s67, 0
	s_add_i32 s66, vcc_hi, s0
	global_load_lds_dwordx4 v[210:211], off
	s_mov_b32 m0, s66
	s_nop 0
	global_load_lds_dwordx4 v196, s[34:35]
	s_add_i32 m0, s66, 0x2000
	s_nop 0
	global_load_lds_dwordx4 v200, s[34:35]
	s_mov_b32 m0, s91
	s_nop 0
	s_add_u32 s100, s94, s92
	s_addc_u32 s101, s95, s93
	global_load_lds_dwordx4 v198, s[100:101]
	s_mov_b32 m0, s30
	s_nop 0
	s_add_u32 s100, s94, s92
	s_addc_u32 s101, s95, s93
	global_load_lds_dwordx4 v202, s[100:101]
	s_waitcnt vmcnt(8) lgkmcnt(0)
	s_barrier
	v_mfma_f32_16x16x32_bf16 v[64:67], v[132:135], v[164:167], v[64:67]
	v_mfma_f32_16x16x32_bf16 v[56:59], v[140:143], v[164:167], v[56:59]
	v_mfma_f32_16x16x32_bf16 v[48:51], v[132:135], v[172:175], v[48:51]
	v_mfma_f32_16x16x32_bf16 v[40:43], v[140:143], v[172:175], v[40:43]
	v_mfma_f32_16x16x32_bf16 v[30:33], v[132:135], v[180:183], v[30:33]
	v_mfma_f32_16x16x32_bf16 v[26:29], v[140:143], v[180:183], v[26:29]
	v_mfma_f32_16x16x32_bf16 v[14:17], v[132:135], v[188:191], v[14:17]
	v_mfma_f32_16x16x32_bf16 v[10:13], v[140:143], v[188:191], v[10:13]
	v_mfma_f32_16x16x32_bf16 v[64:67], v[136:139], v[168:171], v[64:67]
	v_mfma_f32_16x16x32_bf16 v[56:59], v[144:147], v[168:171], v[56:59]
	v_mfma_f32_16x16x32_bf16 v[48:51], v[136:139], v[176:179], v[48:51]
	v_mfma_f32_16x16x32_bf16 v[40:43], v[144:147], v[176:179], v[40:43]
	v_mfma_f32_16x16x32_bf16 v[30:33], v[136:139], v[184:187], v[30:33]
	v_mfma_f32_16x16x32_bf16 v[26:29], v[144:147], v[184:187], v[26:29]
	v_mfma_f32_16x16x32_bf16 v[14:17], v[136:139], v[250:253], v[14:17]
	v_mfma_f32_16x16x32_bf16 v[10:13], v[144:147], v[250:253], v[10:13]
	v_mfma_f32_16x16x32_bf16 v[60:63], v[148:151], v[164:167], v[60:63]
	v_mfma_f32_16x16x32_bf16 v[52:55], v[156:159], v[164:167], v[52:55]
	v_mfma_f32_16x16x32_bf16 v[44:47], v[148:151], v[172:175], v[44:47]
	v_mfma_f32_16x16x32_bf16 v[36:39], v[156:159], v[172:175], v[36:39]
	v_mfma_f32_16x16x32_bf16 v[22:25], v[148:151], v[180:183], v[22:25]
	v_mfma_f32_16x16x32_bf16 v[18:21], v[156:159], v[180:183], v[18:21]
	v_mfma_f32_16x16x32_bf16 v[6:9], v[148:151], v[188:191], v[6:9]
	v_mfma_f32_16x16x32_bf16 v[2:5], v[156:159], v[188:191], v[2:5]
	v_mfma_f32_16x16x32_bf16 v[60:63], v[152:155], v[168:171], v[60:63]
	v_mfma_f32_16x16x32_bf16 v[52:55], v[160:163], v[168:171], v[52:55]
	v_mfma_f32_16x16x32_bf16 v[44:47], v[152:155], v[176:179], v[44:47]
	v_mfma_f32_16x16x32_bf16 v[36:39], v[160:163], v[176:179], v[36:39]
	v_mfma_f32_16x16x32_bf16 v[22:25], v[152:155], v[184:187], v[22:25]
	v_mfma_f32_16x16x32_bf16 v[18:21], v[160:163], v[184:187], v[18:21]
	v_mfma_f32_16x16x32_bf16 v[6:9], v[152:155], v[250:253], v[6:9]
	v_mfma_f32_16x16x32_bf16 v[2:5], v[160:163], v[250:253], v[2:5]
	s_barrier
	s_add_u32 s70, s70, 0x10000
	s_addc_u32 s80, s80, 0
	s_add_u32 s8, s8, 0x100
	s_addc_u32 s9, s9, 0
	s_cmp_lt_i32 vcc_lo, s58
	s_mov_b32 s66, vcc_lo
	s_cbranch_scc1 .LBB0_324
	v_mov_b32_e32 v252, v212
	s_branch .LBB0_235

.LBB0_327:
	s_add_i32 s70, s8, 2
	s_add_u32 s9, s6, 0xfff00080
	s_addc_u32 s10, s7, -1
	s_add_i32 s34, 0, 0x10000
	s_cmp_eq_u32 s59, s8
	s_cselect_b32 s11, s65, s10
	s_cselect_b32 s10, s64, s9
	v_add_u32_e32 v0, s34, v217
	s_cselect_b32 s9, s53, s67
	s_cselect_b32 s8, s52, s66
	s_add_i32 s35, 0, 0x14000
	ds_read_b128 v[132:135], v0
	ds_read_b128 v[136:139], v0 offset:1024
	ds_read_b128 v[140:143], v0 offset:2048
	ds_read_b128 v[144:147], v0 offset:3072
	v_add_u32_e32 v0, s35, v217
	ds_read_b128 v[148:151], v0
	ds_read_b128 v[152:155], v0 offset:1024
	ds_read_b128 v[156:159], v0 offset:2048
	ds_read_b128 v[160:163], v0 offset:3072
	v_add_u32_e32 v0, 0, v216
	s_add_i32 m0, s29, 0xc000
	ds_read_b128 v[164:167], v0
	ds_read_b128 v[168:171], v0 offset:1024
	ds_read_b128 v[172:175], v0 offset:2048
	ds_read_b128 v[176:179], v0 offset:3072
	ds_read_b128 v[180:183], v0 offset:4096
	ds_read_b128 v[184:187], v0 offset:5120
	ds_read_b128 v[188:191], v0 offset:6144
	ds_read_b128 v[250:253], v0 offset:7168
	global_load_lds_dwordx4 v204, s[6:7]
	s_add_i32 m0, s29, 0xe000
	s_nop 0
	global_load_lds_dwordx4 v206, s[6:7]
	s_waitcnt vmcnt(8) lgkmcnt(0)
	s_barrier
	v_mfma_i32_16x16x64_i8 v[128:131], v[132:135], v[164:167], v[128:131]
	v_mfma_i32_16x16x64_i8 v[112:115], v[140:143], v[164:167], v[112:115]
	v_mfma_i32_16x16x64_i8 v[120:123], v[132:135], v[172:175], v[120:123]
	v_mfma_i32_16x16x64_i8 v[96:99], v[140:143], v[172:175], v[96:99]
	v_mfma_i32_16x16x64_i8 v[104:107], v[132:135], v[180:183], v[104:107]
	v_mfma_i32_16x16x64_i8 v[88:91], v[140:143], v[180:183], v[88:91]
	v_mfma_i32_16x16x64_i8 v[84:87], v[132:135], v[188:191], v[84:87]
	v_mfma_i32_16x16x64_i8 v[72:75], v[140:143], v[188:191], v[72:75]
	v_mfma_i32_16x16x64_i8 v[128:131], v[136:139], v[168:171], v[128:131]
	v_mfma_i32_16x16x64_i8 v[112:115], v[144:147], v[168:171], v[112:115]
	v_mfma_i32_16x16x64_i8 v[120:123], v[136:139], v[176:179], v[120:123]
	v_mfma_i32_16x16x64_i8 v[96:99], v[144:147], v[176:179], v[96:99]
	v_mfma_i32_16x16x64_i8 v[104:107], v[136:139], v[184:187], v[104:107]
	v_mfma_i32_16x16x64_i8 v[88:91], v[144:147], v[184:187], v[88:91]
	v_mfma_i32_16x16x64_i8 v[84:87], v[136:139], v[250:253], v[84:87]
	v_mfma_i32_16x16x64_i8 v[72:75], v[144:147], v[250:253], v[72:75]
	v_mfma_i32_16x16x64_i8 v[124:127], v[148:151], v[164:167], v[124:127]
	v_mfma_i32_16x16x64_i8 v[108:111], v[156:159], v[164:167], v[108:111]
	v_mfma_i32_16x16x64_i8 v[116:119], v[148:151], v[172:175], v[116:119]
	v_mfma_i32_16x16x64_i8 v[92:95], v[156:159], v[172:175], v[92:95]
	v_mfma_i32_16x16x64_i8 v[100:103], v[148:151], v[180:183], v[100:103]
	v_mfma_i32_16x16x64_i8 v[80:83], v[156:159], v[180:183], v[80:83]
	v_mfma_i32_16x16x64_i8 v[76:79], v[148:151], v[188:191], v[76:79]
	v_mfma_i32_16x16x64_i8 v[68:71], v[156:159], v[188:191], v[68:71]
	v_mfma_i32_16x16x64_i8 v[124:127], v[152:155], v[168:171], v[124:127]
	v_mfma_i32_16x16x64_i8 v[108:111], v[160:163], v[168:171], v[108:111]
	v_mfma_i32_16x16x64_i8 v[116:119], v[152:155], v[176:179], v[116:119]
	v_mfma_i32_16x16x64_i8 v[92:95], v[160:163], v[176:179], v[92:95]
	v_mfma_i32_16x16x64_i8 v[100:103], v[152:155], v[184:187], v[100:103]
	v_mfma_i32_16x16x64_i8 v[80:83], v[160:163], v[184:187], v[80:83]
	v_mfma_i32_16x16x64_i8 v[76:79], v[152:155], v[250:253], v[76:79]
	v_mfma_i32_16x16x64_i8 v[68:71], v[160:163], v[250:253], v[68:71]
	s_barrier
	s_add_i32 s34, s34, s0
	s_mov_b32 m0, s34
	ds_read_b128 v[164:167], v0 offset:16384
	ds_read_b128 v[168:171], v0 offset:17408
	ds_read_b128 v[172:175], v0 offset:18432
	ds_read_b128 v[176:179], v0 offset:19456
	ds_read_b128 v[180:183], v0 offset:20480
	ds_read_b128 v[184:187], v0 offset:21504
	ds_read_b128 v[188:191], v0 offset:22528
	ds_read_b128 v[250:253], v0 offset:23552
	global_load_lds_dwordx4 v196, s[8:9]
	s_add_i32 m0, s34, 0x2000
	s_add_u32 s94, s8, 0x4000
	s_addc_u32 s95, s9, 0
	s_add_i32 s34, s35, s0
	global_load_lds_dwordx4 v200, s[8:9]
	s_mov_b32 m0, s34
	v_lshl_add_u64 v[194:195], s[10:11], 0, v[202:203]
	global_load_lds_dwordx4 v196, s[94:95]
	s_add_i32 m0, s34, 0x2000
	s_nop 0
	global_load_lds_dwordx4 v200, s[94:95]
	v_lshl_add_u64 v[192:193], s[10:11], 0, v[198:199]
	s_mov_b32 m0, s29
	s_nop 0
	global_load_lds_dwordx4 v198, s[10:11]
	s_waitcnt vmcnt(7) lgkmcnt(0)
	s_barrier
	v_mfma_i32_16x16x64_i8 v[64:67], v[132:135], v[164:167], v[64:67]
	v_mfma_i32_16x16x64_i8 v[56:59], v[140:143], v[164:167], v[56:59]
	v_mfma_i32_16x16x64_i8 v[48:51], v[132:135], v[172:175], v[48:51]
	v_mfma_i32_16x16x64_i8 v[40:43], v[140:143], v[172:175], v[40:43]
	v_mfma_i32_16x16x64_i8 v[30:33], v[132:135], v[180:183], v[30:33]
	v_mfma_i32_16x16x64_i8 v[26:29], v[140:143], v[180:183], v[26:29]
	v_mfma_i32_16x16x64_i8 v[14:17], v[132:135], v[188:191], v[14:17]
	v_mfma_i32_16x16x64_i8 v[10:13], v[140:143], v[188:191], v[10:13]
	v_mfma_i32_16x16x64_i8 v[64:67], v[136:139], v[168:171], v[64:67]
	v_mfma_i32_16x16x64_i8 v[56:59], v[144:147], v[168:171], v[56:59]
	v_mfma_i32_16x16x64_i8 v[48:51], v[136:139], v[176:179], v[48:51]
	v_mfma_i32_16x16x64_i8 v[40:43], v[144:147], v[176:179], v[40:43]
	v_mfma_i32_16x16x64_i8 v[30:33], v[136:139], v[184:187], v[30:33]
	v_mfma_i32_16x16x64_i8 v[26:29], v[144:147], v[184:187], v[26:29]
	v_mfma_i32_16x16x64_i8 v[14:17], v[136:139], v[250:253], v[14:17]
	v_mfma_i32_16x16x64_i8 v[10:13], v[144:147], v[250:253], v[10:13]
	v_mfma_i32_16x16x64_i8 v[60:63], v[148:151], v[164:167], v[60:63]
	v_mfma_i32_16x16x64_i8 v[52:55], v[156:159], v[164:167], v[52:55]
	v_mfma_i32_16x16x64_i8 v[44:47], v[148:151], v[172:175], v[44:47]
	v_mfma_i32_16x16x64_i8 v[36:39], v[156:159], v[172:175], v[36:39]
	v_mfma_i32_16x16x64_i8 v[22:25], v[148:151], v[180:183], v[22:25]
	v_mfma_i32_16x16x64_i8 v[18:21], v[156:159], v[180:183], v[18:21]
	v_mfma_i32_16x16x64_i8 v[6:9], v[148:151], v[188:191], v[6:9]
	v_mfma_i32_16x16x64_i8 v[2:5], v[156:159], v[188:191], v[2:5]
	v_mfma_i32_16x16x64_i8 v[60:63], v[152:155], v[168:171], v[60:63]
	v_mfma_i32_16x16x64_i8 v[52:55], v[160:163], v[168:171], v[52:55]
	v_mfma_i32_16x16x64_i8 v[44:47], v[152:155], v[176:179], v[44:47]
	v_mfma_i32_16x16x64_i8 v[36:39], v[160:163], v[176:179], v[36:39]
	v_mfma_i32_16x16x64_i8 v[22:25], v[152:155], v[184:187], v[22:25]
	v_mfma_i32_16x16x64_i8 v[18:21], v[160:163], v[184:187], v[18:21]
	v_mfma_i32_16x16x64_i8 v[6:9], v[152:155], v[250:253], v[6:9]
	v_mfma_i32_16x16x64_i8 v[2:5], v[160:163], v[250:253], v[2:5]
	s_barrier
	s_mov_b32 m0, s45
	s_nop 0
	global_load_lds_dwordx4 v202, s[10:11]
	s_add_i32 s34, 0, 0x18000
	s_add_i32 s35, 0, 0x1c000
	v_add_u32_e32 v144, s34, v217
	v_add_u32_e32 v160, s35, v217
	ds_read_b128 v[132:135], v144
	ds_read_b128 v[136:139], v144 offset:1024
	ds_read_b128 v[140:143], v144 offset:2048
	ds_read_b128 v[144:147], v144 offset:3072
	ds_read_b128 v[148:151], v160
	ds_read_b128 v[152:155], v160 offset:1024
	ds_read_b128 v[156:159], v160 offset:2048
	ds_read_b128 v[160:163], v160 offset:3072
	s_add_u32 s10, s10, 0x100000
	s_addc_u32 s11, s11, 0
	s_mov_b32 m0, s82
	ds_read_b128 v[164:167], v0 offset:32768
	ds_read_b128 v[168:171], v0 offset:33792
	ds_read_b128 v[172:175], v0 offset:34816
	ds_read_b128 v[176:179], v0 offset:35840
	ds_read_b128 v[180:183], v0 offset:36864
	ds_read_b128 v[184:187], v0 offset:37888
	ds_read_b128 v[188:191], v0 offset:38912
	ds_read_b128 v[250:253], v0 offset:39936
	global_load_lds_dwordx4 v198, s[10:11]
	s_mov_b32 m0, s90
	s_nop 0
	global_load_lds_dwordx4 v202, s[10:11]
	s_waitcnt vmcnt(8) lgkmcnt(0)
	s_barrier
	v_mfma_i32_16x16x64_i8 v[128:131], v[132:135], v[164:167], v[128:131]
	v_mfma_i32_16x16x64_i8 v[112:115], v[140:143], v[164:167], v[112:115]
	v_mfma_i32_16x16x64_i8 v[120:123], v[132:135], v[172:175], v[120:123]
	v_mfma_i32_16x16x64_i8 v[96:99], v[140:143], v[172:175], v[96:99]
	v_mfma_i32_16x16x64_i8 v[104:107], v[132:135], v[180:183], v[104:107]
	v_mfma_i32_16x16x64_i8 v[88:91], v[140:143], v[180:183], v[88:91]
	v_mfma_i32_16x16x64_i8 v[84:87], v[132:135], v[188:191], v[84:87]
	v_mfma_i32_16x16x64_i8 v[72:75], v[140:143], v[188:191], v[72:75]
	v_mfma_i32_16x16x64_i8 v[128:131], v[136:139], v[168:171], v[128:131]
	v_mfma_i32_16x16x64_i8 v[112:115], v[144:147], v[168:171], v[112:115]
	v_mfma_i32_16x16x64_i8 v[120:123], v[136:139], v[176:179], v[120:123]
	v_mfma_i32_16x16x64_i8 v[96:99], v[144:147], v[176:179], v[96:99]
	v_mfma_i32_16x16x64_i8 v[104:107], v[136:139], v[184:187], v[104:107]
	v_mfma_i32_16x16x64_i8 v[88:91], v[144:147], v[184:187], v[88:91]
	v_mfma_i32_16x16x64_i8 v[84:87], v[136:139], v[250:253], v[84:87]
	v_mfma_i32_16x16x64_i8 v[72:75], v[144:147], v[250:253], v[72:75]
	v_mfma_i32_16x16x64_i8 v[124:127], v[148:151], v[164:167], v[124:127]
	v_mfma_i32_16x16x64_i8 v[108:111], v[156:159], v[164:167], v[108:111]
	v_mfma_i32_16x16x64_i8 v[116:119], v[148:151], v[172:175], v[116:119]
	v_mfma_i32_16x16x64_i8 v[92:95], v[156:159], v[172:175], v[92:95]
	v_mfma_i32_16x16x64_i8 v[100:103], v[148:151], v[180:183], v[100:103]
	v_mfma_i32_16x16x64_i8 v[80:83], v[156:159], v[180:183], v[80:83]
	v_mfma_i32_16x16x64_i8 v[76:79], v[148:151], v[188:191], v[76:79]
	v_mfma_i32_16x16x64_i8 v[68:71], v[156:159], v[188:191], v[68:71]
	v_mfma_i32_16x16x64_i8 v[124:127], v[152:155], v[168:171], v[124:127]
	v_mfma_i32_16x16x64_i8 v[108:111], v[160:163], v[168:171], v[108:111]
	v_mfma_i32_16x16x64_i8 v[116:119], v[152:155], v[176:179], v[116:119]
	v_mfma_i32_16x16x64_i8 v[92:95], v[160:163], v[176:179], v[92:95]
	v_mfma_i32_16x16x64_i8 v[100:103], v[152:155], v[184:187], v[100:103]
	v_mfma_i32_16x16x64_i8 v[80:83], v[160:163], v[184:187], v[80:83]
	v_mfma_i32_16x16x64_i8 v[76:79], v[152:155], v[250:253], v[76:79]
	v_mfma_i32_16x16x64_i8 v[68:71], v[160:163], v[250:253], v[68:71]
	s_barrier
	s_add_u32 s10, s8, 0x8000
	s_addc_u32 s11, s9, 0
	s_add_i32 s34, s34, s0
	s_mov_b32 m0, s34
	ds_read_b128 v[164:167], v0 offset:49152
	ds_read_b128 v[168:171], v0 offset:50176
	ds_read_b128 v[172:175], v0 offset:51200
	ds_read_b128 v[176:179], v0 offset:52224
	ds_read_b128 v[180:183], v0 offset:53248
	ds_read_b128 v[184:187], v0 offset:54272
	ds_read_b128 v[188:191], v0 offset:55296
	ds_read_b128 v[250:253], v0 offset:56320
	global_load_lds_dwordx4 v196, s[10:11]
	s_add_i32 m0, s34, 0x2000
	s_add_u32 s8, s8, 0xc000
	v_lshl_add_u64 v[210:211], s[10:11], 0, v[200:201]
	s_addc_u32 s9, s9, 0
	s_add_i32 s10, s35, s0
	global_load_lds_dwordx4 v[210:211], off
	s_mov_b32 m0, s10
	v_lshl_add_u64 v[192:193], v[192:193], 0, s[92:93]
	global_load_lds_dwordx4 v196, s[8:9]
	s_add_i32 m0, s10, 0x2000
	s_nop 0
	global_load_lds_dwordx4 v200, s[8:9]
	s_mov_b32 m0, s91
	s_nop 0
	global_load_lds_dwordx4 v[192:193], off
	v_lshl_add_u64 v[192:193], v[194:195], 0, s[92:93]
	s_mov_b32 m0, s30
	s_nop 0
	global_load_lds_dwordx4 v[192:193], off
	s_waitcnt vmcnt(8) lgkmcnt(0)
	s_barrier
	v_mfma_i32_16x16x64_i8 v[64:67], v[132:135], v[164:167], v[64:67]
	v_mfma_i32_16x16x64_i8 v[56:59], v[140:143], v[164:167], v[56:59]
	v_mfma_i32_16x16x64_i8 v[48:51], v[132:135], v[172:175], v[48:51]
	v_mfma_i32_16x16x64_i8 v[40:43], v[140:143], v[172:175], v[40:43]
	v_mfma_i32_16x16x64_i8 v[30:33], v[132:135], v[180:183], v[30:33]
	v_mfma_i32_16x16x64_i8 v[26:29], v[140:143], v[180:183], v[26:29]
	v_mfma_i32_16x16x64_i8 v[14:17], v[132:135], v[188:191], v[14:17]
	v_mfma_i32_16x16x64_i8 v[10:13], v[140:143], v[188:191], v[10:13]
	v_mfma_i32_16x16x64_i8 v[64:67], v[136:139], v[168:171], v[64:67]
	v_mfma_i32_16x16x64_i8 v[56:59], v[144:147], v[168:171], v[56:59]
	v_mfma_i32_16x16x64_i8 v[48:51], v[136:139], v[176:179], v[48:51]
	v_mfma_i32_16x16x64_i8 v[40:43], v[144:147], v[176:179], v[40:43]
	v_mfma_i32_16x16x64_i8 v[30:33], v[136:139], v[184:187], v[30:33]
	v_mfma_i32_16x16x64_i8 v[26:29], v[144:147], v[184:187], v[26:29]
	v_mfma_i32_16x16x64_i8 v[14:17], v[136:139], v[250:253], v[14:17]
	v_mfma_i32_16x16x64_i8 v[10:13], v[144:147], v[250:253], v[10:13]
	v_mfma_i32_16x16x64_i8 v[60:63], v[148:151], v[164:167], v[60:63]
	v_mfma_i32_16x16x64_i8 v[52:55], v[156:159], v[164:167], v[52:55]
	v_mfma_i32_16x16x64_i8 v[44:47], v[148:151], v[172:175], v[44:47]
	v_mfma_i32_16x16x64_i8 v[36:39], v[156:159], v[172:175], v[36:39]
	v_mfma_i32_16x16x64_i8 v[22:25], v[148:151], v[180:183], v[22:25]
	v_mfma_i32_16x16x64_i8 v[18:21], v[156:159], v[180:183], v[18:21]
	v_mfma_i32_16x16x64_i8 v[6:9], v[148:151], v[188:191], v[6:9]
	v_mfma_i32_16x16x64_i8 v[2:5], v[156:159], v[188:191], v[2:5]
	v_mfma_i32_16x16x64_i8 v[60:63], v[152:155], v[168:171], v[60:63]
	v_mfma_i32_16x16x64_i8 v[52:55], v[160:163], v[168:171], v[52:55]
	v_mfma_i32_16x16x64_i8 v[44:47], v[152:155], v[176:179], v[44:47]
	v_mfma_i32_16x16x64_i8 v[36:39], v[160:163], v[176:179], v[36:39]
	v_mfma_i32_16x16x64_i8 v[22:25], v[152:155], v[184:187], v[22:25]
	v_mfma_i32_16x16x64_i8 v[18:21], v[160:163], v[184:187], v[18:21]
	v_mfma_i32_16x16x64_i8 v[6:9], v[152:155], v[250:253], v[6:9]
	v_mfma_i32_16x16x64_i8 v[2:5], v[160:163], v[250:253], v[2:5]
	s_barrier
	s_add_u32 s66, s66, 0x10000
	s_addc_u32 s67, s67, 0
	s_add_u32 s6, s6, 0x100
	s_addc_u32 s7, s7, 0
	s_cmp_ge_i32 s70, s58
	s_mov_b32 s8, s70
	s_cbranch_scc0 .LBB0_327
	v_mov_b32_e32 v252, v212
	v_cndmask_b32_e64 v0, 0, 1, s[46:47]
	v_cmp_ne_u32_e64 s[6:7], 1, v0
	s_andn2_b64 vcc, exec, s[46:47]
	s_cbranch_vccz .LBB0_236
	s_branch .LBB0_237

.LBB0_707:
	s_add_u32 s34, s50, 0xfff80080
	s_addc_u32 s35, s51, -1
	s_add_i32 s61, 0, 0x10000
	s_cmp_eq_u32 s60, 4
	s_cselect_b32 s55, s23, s35
	s_cselect_b32 s54, s22, s34
	s_cselect_b32 s53, s43, s59
	s_cselect_b32 s52, s42, s21
	s_add_i32 s62, 0, 0x14000
	ds_read_b128 v[164:167], v2 offset:0
	ds_read_b128 v[168:171], v2 offset:1024
	ds_read_b128 v[172:175], v2 offset:2048
	ds_read_b128 v[176:179], v2 offset:3072
	ds_read_b128 v[192:195], v2 offset:16384
	ds_read_b128 v[196:199], v2 offset:17408
	ds_read_b128 v[204:207], v2 offset:18432
	ds_read_b128 v[210:213], v2 offset:19456
	s_add_i32 m0, s29, 0xc000
	ds_read_b128 v[216:219], v203
	ds_read_b128 v[220:223], v203 offset:1024
	ds_read_b128 v[224:227], v203 offset:2048
	ds_read_b128 v[228:231], v203 offset:3072
	ds_read_b128 v[232:235], v203 offset:4096
	ds_read_b128 v[236:239], v203 offset:5120
	ds_read_b128 v[240:243], v203 offset:6144
	ds_read_b128 v[244:247], v203 offset:7168
	global_load_lds_dwordx4 v188, s[50:51]
	s_add_i32 m0, s29, 0xe000
	s_nop 0
	global_load_lds_dwordx4 v190, s[50:51]
	s_waitcnt vmcnt(8) lgkmcnt(0)
	s_barrier
	v_mfma_f32_16x16x32_bf16 v[160:163], v[164:167], v[216:219], v[160:163]
	v_mfma_f32_16x16x32_bf16 v[156:159], v[172:175], v[216:219], v[156:159]
	v_mfma_f32_16x16x32_bf16 v[144:147], v[164:167], v[224:227], v[144:147]
	v_mfma_f32_16x16x32_bf16 v[140:143], v[172:175], v[224:227], v[140:143]
	v_mfma_f32_16x16x32_bf16 v[128:131], v[164:167], v[232:235], v[128:131]
	v_mfma_f32_16x16x32_bf16 v[124:127], v[172:175], v[232:235], v[124:127]
	v_mfma_f32_16x16x32_bf16 v[112:115], v[164:167], v[240:243], v[112:115]
	v_mfma_f32_16x16x32_bf16 v[108:111], v[172:175], v[240:243], v[108:111]
	v_mfma_f32_16x16x32_bf16 v[160:163], v[168:171], v[220:223], v[160:163]
	v_mfma_f32_16x16x32_bf16 v[156:159], v[176:179], v[220:223], v[156:159]
	v_mfma_f32_16x16x32_bf16 v[144:147], v[168:171], v[228:231], v[144:147]
	v_mfma_f32_16x16x32_bf16 v[140:143], v[176:179], v[228:231], v[140:143]
	v_mfma_f32_16x16x32_bf16 v[128:131], v[168:171], v[236:239], v[128:131]
	v_mfma_f32_16x16x32_bf16 v[124:127], v[176:179], v[236:239], v[124:127]
	v_mfma_f32_16x16x32_bf16 v[112:115], v[168:171], v[244:247], v[112:115]
	v_mfma_f32_16x16x32_bf16 v[108:111], v[176:179], v[244:247], v[108:111]
	v_mfma_f32_16x16x32_bf16 v[152:155], v[192:195], v[216:219], v[152:155]
	v_mfma_f32_16x16x32_bf16 v[148:151], v[204:207], v[216:219], v[148:151]
	v_mfma_f32_16x16x32_bf16 v[136:139], v[192:195], v[224:227], v[136:139]
	v_mfma_f32_16x16x32_bf16 v[132:135], v[204:207], v[224:227], v[132:135]
	v_mfma_f32_16x16x32_bf16 v[120:123], v[192:195], v[232:235], v[120:123]
	v_mfma_f32_16x16x32_bf16 v[116:119], v[204:207], v[232:235], v[116:119]
	v_mfma_f32_16x16x32_bf16 v[104:107], v[192:195], v[240:243], v[104:107]
	v_mfma_f32_16x16x32_bf16 v[100:103], v[204:207], v[240:243], v[100:103]
	v_mfma_f32_16x16x32_bf16 v[152:155], v[196:199], v[220:223], v[152:155]
	v_mfma_f32_16x16x32_bf16 v[148:151], v[210:213], v[220:223], v[148:151]
	v_mfma_f32_16x16x32_bf16 v[136:139], v[196:199], v[228:231], v[136:139]
	v_mfma_f32_16x16x32_bf16 v[132:135], v[210:213], v[228:231], v[132:135]
	v_mfma_f32_16x16x32_bf16 v[120:123], v[196:199], v[236:239], v[120:123]
	v_mfma_f32_16x16x32_bf16 v[116:119], v[210:213], v[236:239], v[116:119]
	v_mfma_f32_16x16x32_bf16 v[104:107], v[196:199], v[244:247], v[104:107]
	v_mfma_f32_16x16x32_bf16 v[100:103], v[210:213], v[244:247], v[100:103]
	s_barrier
	s_add_i32 s34, s61, s0
	s_mov_b32 m0, s34
	ds_read_b128 v[216:219], v203 offset:16384
	ds_read_b128 v[220:223], v203 offset:17408
	ds_read_b128 v[224:227], v203 offset:18432
	ds_read_b128 v[228:231], v203 offset:19456
	ds_read_b128 v[232:235], v203 offset:20480
	ds_read_b128 v[236:239], v203 offset:21504
	ds_read_b128 v[240:243], v203 offset:22528
	ds_read_b128 v[244:247], v203 offset:23552
	global_load_lds_dwordx4 v180, s[52:53]
	s_add_i32 m0, s34, 0x2000
	s_add_u32 s34, s52, 0x4000
	s_addc_u32 s35, s53, 0
	s_add_i32 s61, s62, s0
	global_load_lds_dwordx4 v184, s[52:53]
	s_mov_b32 m0, s61
	v_lshl_add_u64 v[248:249], s[54:55], 0, v[186:187]
	global_load_lds_dwordx4 v180, s[34:35]
	s_add_i32 m0, s61, 0x2000
	s_nop 0
	global_load_lds_dwordx4 v184, s[34:35]
	v_lshl_add_u64 v[200:201], s[54:55], 0, v[182:183]
	s_mov_b32 m0, s29
	s_nop 0
	global_load_lds_dwordx4 v182, s[54:55]
	s_waitcnt vmcnt(7) lgkmcnt(0)
	s_barrier
	v_mfma_f32_16x16x32_bf16 v[96:99], v[164:167], v[216:219], v[96:99]
	v_mfma_f32_16x16x32_bf16 v[92:95], v[172:175], v[216:219], v[92:95]
	v_mfma_f32_16x16x32_bf16 v[84:87], v[164:167], v[224:227], v[84:87]
	v_mfma_f32_16x16x32_bf16 v[76:79], v[172:175], v[224:227], v[76:79]
	v_mfma_f32_16x16x32_bf16 v[68:71], v[164:167], v[232:235], v[68:71]
	v_mfma_f32_16x16x32_bf16 v[60:63], v[172:175], v[232:235], v[60:63]
	v_mfma_f32_16x16x32_bf16 v[52:55], v[164:167], v[240:243], v[52:55]
	v_mfma_f32_16x16x32_bf16 v[44:47], v[172:175], v[240:243], v[44:47]
	v_mfma_f32_16x16x32_bf16 v[96:99], v[168:171], v[220:223], v[96:99]
	v_mfma_f32_16x16x32_bf16 v[92:95], v[176:179], v[220:223], v[92:95]
	v_mfma_f32_16x16x32_bf16 v[84:87], v[168:171], v[228:231], v[84:87]
	v_mfma_f32_16x16x32_bf16 v[76:79], v[176:179], v[228:231], v[76:79]
	v_mfma_f32_16x16x32_bf16 v[68:71], v[168:171], v[236:239], v[68:71]
	v_mfma_f32_16x16x32_bf16 v[60:63], v[176:179], v[236:239], v[60:63]
	v_mfma_f32_16x16x32_bf16 v[52:55], v[168:171], v[244:247], v[52:55]
	v_mfma_f32_16x16x32_bf16 v[44:47], v[176:179], v[244:247], v[44:47]
	v_mfma_f32_16x16x32_bf16 v[88:91], v[192:195], v[216:219], v[88:91]
	v_mfma_f32_16x16x32_bf16 v[80:83], v[204:207], v[216:219], v[80:83]
	v_mfma_f32_16x16x32_bf16 v[72:75], v[192:195], v[224:227], v[72:75]
	v_mfma_f32_16x16x32_bf16 v[64:67], v[204:207], v[224:227], v[64:67]
	v_mfma_f32_16x16x32_bf16 v[56:59], v[192:195], v[232:235], v[56:59]
	v_mfma_f32_16x16x32_bf16 v[48:51], v[204:207], v[232:235], v[48:51]
	v_mfma_f32_16x16x32_bf16 v[40:43], v[192:195], v[240:243], v[40:43]
	v_mfma_f32_16x16x32_bf16 v[36:39], v[204:207], v[240:243], v[36:39]
	v_mfma_f32_16x16x32_bf16 v[88:91], v[196:199], v[220:223], v[88:91]
	v_mfma_f32_16x16x32_bf16 v[80:83], v[210:213], v[220:223], v[80:83]
	v_mfma_f32_16x16x32_bf16 v[72:75], v[196:199], v[228:231], v[72:75]
	v_mfma_f32_16x16x32_bf16 v[64:67], v[210:213], v[228:231], v[64:67]
	v_mfma_f32_16x16x32_bf16 v[56:59], v[196:199], v[236:239], v[56:59]
	v_mfma_f32_16x16x32_bf16 v[48:51], v[210:213], v[236:239], v[48:51]
	v_mfma_f32_16x16x32_bf16 v[40:43], v[196:199], v[244:247], v[40:43]
	v_mfma_f32_16x16x32_bf16 v[36:39], v[210:213], v[244:247], v[36:39]
	s_barrier
	s_mov_b32 m0, s45
	s_nop 0
	global_load_lds_dwordx4 v186, s[54:55]
	s_add_i32 s61, 0, 0x18000
	s_add_i32 s62, 0, 0x1c000
	ds_read_b128 v[164:167], v2 offset:32768
	ds_read_b128 v[168:171], v2 offset:33792
	ds_read_b128 v[172:175], v2 offset:34816
	ds_read_b128 v[176:179], v2 offset:35840
	ds_read_b128 v[192:195], v2 offset:49152
	ds_read_b128 v[196:199], v2 offset:50176
	ds_read_b128 v[204:207], v2 offset:51200
	ds_read_b128 v[210:213], v2 offset:52224
	s_add_u32 s34, s54, 0x80000
	s_addc_u32 s35, s55, 0
	s_mov_b32 m0, s82
	ds_read_b128 v[216:219], v203 offset:32768
	ds_read_b128 v[220:223], v203 offset:33792
	ds_read_b128 v[224:227], v203 offset:34816
	ds_read_b128 v[228:231], v203 offset:35840
	ds_read_b128 v[232:235], v203 offset:36864
	ds_read_b128 v[236:239], v203 offset:37888
	ds_read_b128 v[240:243], v203 offset:38912
	ds_read_b128 v[244:247], v203 offset:39936
	global_load_lds_dwordx4 v182, s[34:35]
	s_mov_b32 m0, s90
	s_nop 0
	global_load_lds_dwordx4 v186, s[34:35]
	s_waitcnt vmcnt(8) lgkmcnt(0)
	s_barrier
	v_mfma_f32_16x16x32_bf16 v[160:163], v[164:167], v[216:219], v[160:163]
	v_mfma_f32_16x16x32_bf16 v[156:159], v[172:175], v[216:219], v[156:159]
	v_mfma_f32_16x16x32_bf16 v[144:147], v[164:167], v[224:227], v[144:147]
	v_mfma_f32_16x16x32_bf16 v[140:143], v[172:175], v[224:227], v[140:143]
	v_mfma_f32_16x16x32_bf16 v[128:131], v[164:167], v[232:235], v[128:131]
	v_mfma_f32_16x16x32_bf16 v[124:127], v[172:175], v[232:235], v[124:127]
	v_mfma_f32_16x16x32_bf16 v[112:115], v[164:167], v[240:243], v[112:115]
	v_mfma_f32_16x16x32_bf16 v[108:111], v[172:175], v[240:243], v[108:111]
	v_mfma_f32_16x16x32_bf16 v[160:163], v[168:171], v[220:223], v[160:163]
	v_mfma_f32_16x16x32_bf16 v[156:159], v[176:179], v[220:223], v[156:159]
	v_mfma_f32_16x16x32_bf16 v[144:147], v[168:171], v[228:231], v[144:147]
	v_mfma_f32_16x16x32_bf16 v[140:143], v[176:179], v[228:231], v[140:143]
	v_mfma_f32_16x16x32_bf16 v[128:131], v[168:171], v[236:239], v[128:131]
	v_mfma_f32_16x16x32_bf16 v[124:127], v[176:179], v[236:239], v[124:127]
	v_mfma_f32_16x16x32_bf16 v[112:115], v[168:171], v[244:247], v[112:115]
	v_mfma_f32_16x16x32_bf16 v[108:111], v[176:179], v[244:247], v[108:111]
	v_mfma_f32_16x16x32_bf16 v[152:155], v[192:195], v[216:219], v[152:155]
	v_mfma_f32_16x16x32_bf16 v[148:151], v[204:207], v[216:219], v[148:151]
	v_mfma_f32_16x16x32_bf16 v[136:139], v[192:195], v[224:227], v[136:139]
	v_mfma_f32_16x16x32_bf16 v[132:135], v[204:207], v[224:227], v[132:135]
	v_mfma_f32_16x16x32_bf16 v[120:123], v[192:195], v[232:235], v[120:123]
	v_mfma_f32_16x16x32_bf16 v[116:119], v[204:207], v[232:235], v[116:119]
	v_mfma_f32_16x16x32_bf16 v[104:107], v[192:195], v[240:243], v[104:107]
	v_mfma_f32_16x16x32_bf16 v[100:103], v[204:207], v[240:243], v[100:103]
	v_mfma_f32_16x16x32_bf16 v[152:155], v[196:199], v[220:223], v[152:155]
	v_mfma_f32_16x16x32_bf16 v[148:151], v[210:213], v[220:223], v[148:151]
	v_mfma_f32_16x16x32_bf16 v[136:139], v[196:199], v[228:231], v[136:139]
	v_mfma_f32_16x16x32_bf16 v[132:135], v[210:213], v[228:231], v[132:135]
	v_mfma_f32_16x16x32_bf16 v[120:123], v[196:199], v[236:239], v[120:123]
	v_mfma_f32_16x16x32_bf16 v[116:119], v[210:213], v[236:239], v[116:119]
	v_mfma_f32_16x16x32_bf16 v[104:107], v[196:199], v[244:247], v[104:107]
	v_mfma_f32_16x16x32_bf16 v[100:103], v[210:213], v[244:247], v[100:103]
	s_barrier
	s_add_u32 s34, s52, 0x8000
	s_addc_u32 s35, s53, 0
	s_add_i32 s54, s61, s0
	s_mov_b32 m0, s54
	ds_read_b128 v[216:219], v203 offset:49152
	ds_read_b128 v[220:223], v203 offset:50176
	ds_read_b128 v[224:227], v203 offset:51200
	ds_read_b128 v[228:231], v203 offset:52224
	ds_read_b128 v[232:235], v203 offset:53248
	ds_read_b128 v[236:239], v203 offset:54272
	ds_read_b128 v[240:243], v203 offset:55296
	ds_read_b128 v[244:247], v203 offset:56320
	global_load_lds_dwordx4 v180, s[34:35]
	s_add_i32 m0, s54, 0x2000
	v_lshl_add_u64 v[250:251], s[34:35], 0, v[184:185]
	s_add_u32 s34, s52, 0xc000
	s_addc_u32 s35, s53, 0
	s_add_i32 s52, s62, s0
	global_load_lds_dwordx4 v[250:251], off
	s_mov_b32 m0, s52
	v_lshl_add_u64 v[200:201], v[200:201], 0, s[92:93]
	global_load_lds_dwordx4 v180, s[34:35]
	s_add_i32 m0, s52, 0x2000
	s_nop 0
	global_load_lds_dwordx4 v184, s[34:35]
	s_mov_b32 m0, s91
	s_nop 0
	global_load_lds_dwordx4 v[200:201], off
	v_lshl_add_u64 v[200:201], v[248:249], 0, s[92:93]
	s_mov_b32 m0, s30
	s_nop 0
	global_load_lds_dwordx4 v[200:201], off
	s_waitcnt vmcnt(8) lgkmcnt(0)
	s_barrier
	v_mfma_f32_16x16x32_bf16 v[96:99], v[164:167], v[216:219], v[96:99]
	v_mfma_f32_16x16x32_bf16 v[92:95], v[172:175], v[216:219], v[92:95]
	v_mfma_f32_16x16x32_bf16 v[84:87], v[164:167], v[224:227], v[84:87]
	v_mfma_f32_16x16x32_bf16 v[76:79], v[172:175], v[224:227], v[76:79]
	v_mfma_f32_16x16x32_bf16 v[68:71], v[164:167], v[232:235], v[68:71]
	v_mfma_f32_16x16x32_bf16 v[60:63], v[172:175], v[232:235], v[60:63]
	v_mfma_f32_16x16x32_bf16 v[52:55], v[164:167], v[240:243], v[52:55]
	v_mfma_f32_16x16x32_bf16 v[44:47], v[172:175], v[240:243], v[44:47]
	v_mfma_f32_16x16x32_bf16 v[96:99], v[168:171], v[220:223], v[96:99]
	v_mfma_f32_16x16x32_bf16 v[92:95], v[176:179], v[220:223], v[92:95]
	v_mfma_f32_16x16x32_bf16 v[84:87], v[168:171], v[228:231], v[84:87]
	v_mfma_f32_16x16x32_bf16 v[76:79], v[176:179], v[228:231], v[76:79]
	v_mfma_f32_16x16x32_bf16 v[68:71], v[168:171], v[236:239], v[68:71]
	v_mfma_f32_16x16x32_bf16 v[60:63], v[176:179], v[236:239], v[60:63]
	v_mfma_f32_16x16x32_bf16 v[52:55], v[168:171], v[244:247], v[52:55]
	v_mfma_f32_16x16x32_bf16 v[44:47], v[176:179], v[244:247], v[44:47]
	v_mfma_f32_16x16x32_bf16 v[88:91], v[192:195], v[216:219], v[88:91]
	v_mfma_f32_16x16x32_bf16 v[80:83], v[204:207], v[216:219], v[80:83]
	v_mfma_f32_16x16x32_bf16 v[72:75], v[192:195], v[224:227], v[72:75]
	v_mfma_f32_16x16x32_bf16 v[64:67], v[204:207], v[224:227], v[64:67]
	v_mfma_f32_16x16x32_bf16 v[56:59], v[192:195], v[232:235], v[56:59]
	v_mfma_f32_16x16x32_bf16 v[48:51], v[204:207], v[232:235], v[48:51]
	v_mfma_f32_16x16x32_bf16 v[40:43], v[192:195], v[240:243], v[40:43]
	v_mfma_f32_16x16x32_bf16 v[36:39], v[204:207], v[240:243], v[36:39]
	v_mfma_f32_16x16x32_bf16 v[88:91], v[196:199], v[220:223], v[88:91]
	v_mfma_f32_16x16x32_bf16 v[80:83], v[210:213], v[220:223], v[80:83]
	v_mfma_f32_16x16x32_bf16 v[72:75], v[196:199], v[228:231], v[72:75]
	v_mfma_f32_16x16x32_bf16 v[64:67], v[210:213], v[228:231], v[64:67]
	v_mfma_f32_16x16x32_bf16 v[56:59], v[196:199], v[236:239], v[56:59]
	v_mfma_f32_16x16x32_bf16 v[48:51], v[210:213], v[236:239], v[48:51]
	v_mfma_f32_16x16x32_bf16 v[40:43], v[196:199], v[244:247], v[40:43]
	v_mfma_f32_16x16x32_bf16 v[36:39], v[210:213], v[244:247], v[36:39]
	s_barrier
	s_add_i32 s60, s60, 2
	s_add_u32 s21, s21, 0x10000
	s_addc_u32 s59, s59, 0
	s_add_u32 s50, s50, 0x100
	s_addc_u32 s51, s51, 0
	s_cmp_gt_u32 s60, 5
	s_cbranch_scc0 .LBB0_707
	s_and_b64 vcc, exec, s[46:47]
	s_cbranch_vccz .LBB0_710
	s_barrier

.LBB0_788:
	s_add_u32 s34, s48, 0xfff80080
	s_addc_u32 s35, s49, -1
	s_add_i32 s57, 0, 0x10000
	s_cmp_eq_u32 s56, 28
	s_cselect_b32 s55, s23, s35
	s_cselect_b32 s54, s22, s34
	s_cselect_b32 s53, s43, s51
	s_cselect_b32 s52, s42, s15
	s_add_i32 s69, 0, 0x14000
	ds_read_b128 v[136:139], v200 offset:0
	ds_read_b128 v[140:143], v200 offset:1024
	ds_read_b128 v[144:147], v200 offset:2048
	ds_read_b128 v[148:151], v200 offset:3072
	ds_read_b128 v[152:155], v200 offset:16384
	ds_read_b128 v[156:159], v200 offset:17408
	ds_read_b128 v[160:163], v200 offset:18432
	ds_read_b128 v[174:177], v200 offset:19456
	s_add_i32 m0, s29, 0xc000
	ds_read_b128 v[178:181], v199
	ds_read_b128 v[182:185], v199 offset:1024
	ds_read_b128 v[186:189], v199 offset:2048
	ds_read_b128 v[190:193], v199 offset:3072
	ds_read_b128 v[194:197], v199 offset:4096
	ds_read_b128 v[210:213], v199 offset:5120
	ds_read_b128 v[240:243], v199 offset:6144
	ds_read_b128 v[244:247], v199 offset:7168
	global_load_lds_dwordx4 v170, s[48:49]
	s_add_i32 m0, s29, 0xe000
	s_nop 0
	global_load_lds_dwordx4 v172, s[48:49]
	s_waitcnt vmcnt(8) lgkmcnt(0)
	s_barrier
	v_mfma_f32_16x16x32_bf16 v[132:135], v[136:139], v[178:181], v[132:135]
	v_mfma_f32_16x16x32_bf16 v[128:131], v[144:147], v[178:181], v[128:131]
	v_mfma_f32_16x16x32_bf16 v[124:127], v[136:139], v[186:189], v[124:127]
	v_mfma_f32_16x16x32_bf16 v[120:123], v[144:147], v[186:189], v[120:123]
	v_mfma_f32_16x16x32_bf16 v[116:119], v[136:139], v[194:197], v[116:119]
	v_mfma_f32_16x16x32_bf16 v[112:115], v[144:147], v[194:197], v[112:115]
	v_mfma_f32_16x16x32_bf16 v[108:111], v[136:139], v[240:243], v[108:111]
	v_mfma_f32_16x16x32_bf16 v[104:107], v[144:147], v[240:243], v[104:107]
	v_mfma_f32_16x16x32_bf16 v[132:135], v[140:143], v[182:185], v[132:135]
	v_mfma_f32_16x16x32_bf16 v[128:131], v[148:151], v[182:185], v[128:131]
	v_mfma_f32_16x16x32_bf16 v[124:127], v[140:143], v[190:193], v[124:127]
	v_mfma_f32_16x16x32_bf16 v[120:123], v[148:151], v[190:193], v[120:123]
	v_mfma_f32_16x16x32_bf16 v[116:119], v[140:143], v[210:213], v[116:119]
	v_mfma_f32_16x16x32_bf16 v[112:115], v[148:151], v[210:213], v[112:115]
	v_mfma_f32_16x16x32_bf16 v[108:111], v[140:143], v[244:247], v[108:111]
	v_mfma_f32_16x16x32_bf16 v[104:107], v[148:151], v[244:247], v[104:107]
	v_mfma_f32_16x16x32_bf16 v[100:103], v[152:155], v[178:181], v[100:103]
	v_mfma_f32_16x16x32_bf16 v[96:99], v[160:163], v[178:181], v[96:99]
	v_mfma_f32_16x16x32_bf16 v[92:95], v[152:155], v[186:189], v[92:95]
	v_mfma_f32_16x16x32_bf16 v[88:91], v[160:163], v[186:189], v[88:91]
	v_mfma_f32_16x16x32_bf16 v[84:87], v[152:155], v[194:197], v[84:87]
	v_mfma_f32_16x16x32_bf16 v[80:83], v[160:163], v[194:197], v[80:83]
	v_mfma_f32_16x16x32_bf16 v[72:75], v[152:155], v[240:243], v[72:75]
	v_mfma_f32_16x16x32_bf16 v[64:67], v[160:163], v[240:243], v[64:67]
	v_mfma_f32_16x16x32_bf16 v[100:103], v[156:159], v[182:185], v[100:103]
	v_mfma_f32_16x16x32_bf16 v[96:99], v[174:177], v[182:185], v[96:99]
	v_mfma_f32_16x16x32_bf16 v[92:95], v[156:159], v[190:193], v[92:95]
	v_mfma_f32_16x16x32_bf16 v[88:91], v[174:177], v[190:193], v[88:91]
	v_mfma_f32_16x16x32_bf16 v[84:87], v[156:159], v[210:213], v[84:87]
	v_mfma_f32_16x16x32_bf16 v[80:83], v[174:177], v[210:213], v[80:83]
	v_mfma_f32_16x16x32_bf16 v[72:75], v[156:159], v[244:247], v[72:75]
	v_mfma_f32_16x16x32_bf16 v[64:67], v[174:177], v[244:247], v[64:67]
	s_barrier
	s_add_i32 s34, s57, s0
	s_mov_b32 m0, s34
	ds_read_b128 v[178:181], v199 offset:16384
	ds_read_b128 v[182:185], v199 offset:17408
	ds_read_b128 v[186:189], v199 offset:18432
	ds_read_b128 v[190:193], v199 offset:19456
	ds_read_b128 v[194:197], v199 offset:20480
	ds_read_b128 v[210:213], v199 offset:21504
	ds_read_b128 v[240:243], v199 offset:22528
	ds_read_b128 v[244:247], v199 offset:23552
	global_load_lds_dwordx4 v32, s[52:53]
	s_add_i32 m0, s34, 0x2000
	s_add_u32 s34, s52, 0x4000
	s_addc_u32 s35, s53, 0
	s_add_i32 s57, s69, s0
	global_load_lds_dwordx4 v166, s[52:53]
	s_mov_b32 m0, s57
	v_lshl_add_u64 v[248:249], s[54:55], 0, v[164:165]
	global_load_lds_dwordx4 v32, s[34:35]
	s_add_i32 m0, s57, 0x2000
	v_lshl_add_u64 v[250:251], s[54:55], 0, v[168:169]
	global_load_lds_dwordx4 v166, s[34:35]
	s_mov_b32 m0, s29
	s_nop 0
	global_load_lds_dwordx4 v164, s[54:55]
	s_waitcnt vmcnt(7) lgkmcnt(0)
	s_barrier
	v_mfma_f32_16x16x32_bf16 v[76:79], v[136:139], v[178:181], v[76:79]
	v_mfma_f32_16x16x32_bf16 v[68:71], v[144:147], v[178:181], v[68:71]
	v_mfma_f32_16x16x32_bf16 v[60:63], v[136:139], v[186:189], v[60:63]
	v_mfma_f32_16x16x32_bf16 v[56:59], v[144:147], v[186:189], v[56:59]
	v_mfma_f32_16x16x32_bf16 v[52:55], v[136:139], v[194:197], v[52:55]
	v_mfma_f32_16x16x32_bf16 v[48:51], v[144:147], v[194:197], v[48:51]
	v_mfma_f32_16x16x32_bf16 v[44:47], v[136:139], v[240:243], v[44:47]
	v_mfma_f32_16x16x32_bf16 v[40:43], v[144:147], v[240:243], v[40:43]
	v_mfma_f32_16x16x32_bf16 v[76:79], v[140:143], v[182:185], v[76:79]
	v_mfma_f32_16x16x32_bf16 v[68:71], v[148:151], v[182:185], v[68:71]
	v_mfma_f32_16x16x32_bf16 v[60:63], v[140:143], v[190:193], v[60:63]
	v_mfma_f32_16x16x32_bf16 v[56:59], v[148:151], v[190:193], v[56:59]
	v_mfma_f32_16x16x32_bf16 v[52:55], v[140:143], v[210:213], v[52:55]
	v_mfma_f32_16x16x32_bf16 v[48:51], v[148:151], v[210:213], v[48:51]
	v_mfma_f32_16x16x32_bf16 v[44:47], v[140:143], v[244:247], v[44:47]
	v_mfma_f32_16x16x32_bf16 v[40:43], v[148:151], v[244:247], v[40:43]
	v_mfma_f32_16x16x32_bf16 v[36:39], v[152:155], v[178:181], v[36:39]
	v_mfma_f32_16x16x32_bf16 v[28:31], v[160:163], v[178:181], v[28:31]
	v_mfma_f32_16x16x32_bf16 v[24:27], v[152:155], v[186:189], v[24:27]
	v_mfma_f32_16x16x32_bf16 v[20:23], v[160:163], v[186:189], v[20:23]
	v_mfma_f32_16x16x32_bf16 v[16:19], v[152:155], v[194:197], v[16:19]
	v_mfma_f32_16x16x32_bf16 v[12:15], v[160:163], v[194:197], v[12:15]
	v_mfma_f32_16x16x32_bf16 v[8:11], v[152:155], v[240:243], v[8:11]
	v_mfma_f32_16x16x32_bf16 v[2:5], v[160:163], v[240:243], v[4:7]
	v_mfma_f32_16x16x32_bf16 v[36:39], v[156:159], v[182:185], v[36:39]
	v_mfma_f32_16x16x32_bf16 v[28:31], v[174:177], v[182:185], v[28:31]
	v_mfma_f32_16x16x32_bf16 v[24:27], v[156:159], v[190:193], v[24:27]
	v_mfma_f32_16x16x32_bf16 v[20:23], v[174:177], v[190:193], v[20:23]
	v_mfma_f32_16x16x32_bf16 v[16:19], v[156:159], v[210:213], v[16:19]
	v_mfma_f32_16x16x32_bf16 v[12:15], v[174:177], v[210:213], v[12:15]
	v_mfma_f32_16x16x32_bf16 v[8:11], v[156:159], v[244:247], v[8:11]
	v_mfma_f32_16x16x32_bf16 v[2:5], v[174:177], v[244:247], v[2:5]
	s_barrier
	s_mov_b32 m0, s45
	s_nop 0
	global_load_lds_dwordx4 v168, s[54:55]
	s_add_i32 s57, 0, 0x18000
	s_add_i32 s69, 0, 0x1c000
	ds_read_b128 v[136:139], v200 offset:32768
	ds_read_b128 v[140:143], v200 offset:33792
	ds_read_b128 v[144:147], v200 offset:34816
	ds_read_b128 v[148:151], v200 offset:35840
	ds_read_b128 v[152:155], v200 offset:49152
	ds_read_b128 v[156:159], v200 offset:50176
	ds_read_b128 v[160:163], v200 offset:51200
	ds_read_b128 v[174:177], v200 offset:52224
	s_add_u32 s34, s54, 0x80000
	s_addc_u32 s35, s55, 0
	s_mov_b32 m0, s82
	ds_read_b128 v[178:181], v199 offset:32768
	ds_read_b128 v[182:185], v199 offset:33792
	ds_read_b128 v[186:189], v199 offset:34816
	ds_read_b128 v[190:193], v199 offset:35840
	ds_read_b128 v[194:197], v199 offset:36864
	ds_read_b128 v[210:213], v199 offset:37888
	ds_read_b128 v[240:243], v199 offset:38912
	ds_read_b128 v[244:247], v199 offset:39936
	global_load_lds_dwordx4 v164, s[34:35]
	s_mov_b32 m0, s90
	s_nop 0
	global_load_lds_dwordx4 v168, s[34:35]
	s_waitcnt vmcnt(8) lgkmcnt(0)
	s_barrier
	v_mfma_f32_16x16x32_bf16 v[132:135], v[136:139], v[178:181], v[132:135]
	v_mfma_f32_16x16x32_bf16 v[128:131], v[144:147], v[178:181], v[128:131]
	v_mfma_f32_16x16x32_bf16 v[124:127], v[136:139], v[186:189], v[124:127]
	v_mfma_f32_16x16x32_bf16 v[120:123], v[144:147], v[186:189], v[120:123]
	v_mfma_f32_16x16x32_bf16 v[116:119], v[136:139], v[194:197], v[116:119]
	v_mfma_f32_16x16x32_bf16 v[112:115], v[144:147], v[194:197], v[112:115]
	v_mfma_f32_16x16x32_bf16 v[108:111], v[136:139], v[240:243], v[108:111]
	v_mfma_f32_16x16x32_bf16 v[104:107], v[144:147], v[240:243], v[104:107]
	v_mfma_f32_16x16x32_bf16 v[132:135], v[140:143], v[182:185], v[132:135]
	v_mfma_f32_16x16x32_bf16 v[128:131], v[148:151], v[182:185], v[128:131]
	v_mfma_f32_16x16x32_bf16 v[124:127], v[140:143], v[190:193], v[124:127]
	v_mfma_f32_16x16x32_bf16 v[120:123], v[148:151], v[190:193], v[120:123]
	v_mfma_f32_16x16x32_bf16 v[116:119], v[140:143], v[210:213], v[116:119]
	v_mfma_f32_16x16x32_bf16 v[112:115], v[148:151], v[210:213], v[112:115]
	v_mfma_f32_16x16x32_bf16 v[108:111], v[140:143], v[244:247], v[108:111]
	v_mfma_f32_16x16x32_bf16 v[104:107], v[148:151], v[244:247], v[104:107]
	v_mfma_f32_16x16x32_bf16 v[100:103], v[152:155], v[178:181], v[100:103]
	v_mfma_f32_16x16x32_bf16 v[96:99], v[160:163], v[178:181], v[96:99]
	v_mfma_f32_16x16x32_bf16 v[92:95], v[152:155], v[186:189], v[92:95]
	v_mfma_f32_16x16x32_bf16 v[88:91], v[160:163], v[186:189], v[88:91]
	v_mfma_f32_16x16x32_bf16 v[84:87], v[152:155], v[194:197], v[84:87]
	v_mfma_f32_16x16x32_bf16 v[80:83], v[160:163], v[194:197], v[80:83]
	v_mfma_f32_16x16x32_bf16 v[72:75], v[152:155], v[240:243], v[72:75]
	v_mfma_f32_16x16x32_bf16 v[64:67], v[160:163], v[240:243], v[64:67]
	v_mfma_f32_16x16x32_bf16 v[100:103], v[156:159], v[182:185], v[100:103]
	v_mfma_f32_16x16x32_bf16 v[96:99], v[174:177], v[182:185], v[96:99]
	v_mfma_f32_16x16x32_bf16 v[92:95], v[156:159], v[190:193], v[92:95]
	v_mfma_f32_16x16x32_bf16 v[88:91], v[174:177], v[190:193], v[88:91]
	v_mfma_f32_16x16x32_bf16 v[84:87], v[156:159], v[210:213], v[84:87]
	v_mfma_f32_16x16x32_bf16 v[80:83], v[174:177], v[210:213], v[80:83]
	v_mfma_f32_16x16x32_bf16 v[72:75], v[156:159], v[244:247], v[72:75]
	v_mfma_f32_16x16x32_bf16 v[64:67], v[174:177], v[244:247], v[64:67]
	s_barrier
	s_add_u32 s34, s52, 0x8000
	s_addc_u32 s35, s53, 0
	s_add_i32 s54, s57, s0
	s_mov_b32 m0, s54
	ds_read_b128 v[178:181], v199 offset:49152
	ds_read_b128 v[182:185], v199 offset:50176
	ds_read_b128 v[186:189], v199 offset:51200
	ds_read_b128 v[190:193], v199 offset:52224
	ds_read_b128 v[194:197], v199 offset:53248
	ds_read_b128 v[210:213], v199 offset:54272
	ds_read_b128 v[240:243], v199 offset:55296
	ds_read_b128 v[244:247], v199 offset:56320
	global_load_lds_dwordx4 v32, s[34:35]
	s_add_i32 m0, s54, 0x2000
	v_lshl_add_u64 v[6:7], s[34:35], 0, v[166:167]
	s_add_u32 s34, s52, 0xc000
	s_addc_u32 s35, s53, 0
	s_add_i32 s52, s69, s0
	global_load_lds_dwordx4 v[6:7], off
	s_mov_b32 m0, s52
	s_nop 0
	global_load_lds_dwordx4 v32, s[34:35]
	s_add_i32 m0, s52, 0x2000
	s_nop 0
	global_load_lds_dwordx4 v166, s[34:35]
	v_lshl_add_u64 v[6:7], v[248:249], 0, s[92:93]
	s_mov_b32 m0, s91
	s_nop 0
	global_load_lds_dwordx4 v[6:7], off
	v_lshl_add_u64 v[6:7], v[250:251], 0, s[92:93]
	s_mov_b32 m0, s30
	s_nop 0
	global_load_lds_dwordx4 v[6:7], off
	s_waitcnt vmcnt(8) lgkmcnt(0)
	s_barrier
	v_mfma_f32_16x16x32_bf16 v[76:79], v[136:139], v[178:181], v[76:79]
	v_mfma_f32_16x16x32_bf16 v[68:71], v[144:147], v[178:181], v[68:71]
	v_mfma_f32_16x16x32_bf16 v[60:63], v[136:139], v[186:189], v[60:63]
	v_mfma_f32_16x16x32_bf16 v[56:59], v[144:147], v[186:189], v[56:59]
	v_mfma_f32_16x16x32_bf16 v[52:55], v[136:139], v[194:197], v[52:55]
	v_mfma_f32_16x16x32_bf16 v[48:51], v[144:147], v[194:197], v[48:51]
	v_mfma_f32_16x16x32_bf16 v[44:47], v[136:139], v[240:243], v[44:47]
	v_mfma_f32_16x16x32_bf16 v[40:43], v[144:147], v[240:243], v[40:43]
	v_mfma_f32_16x16x32_bf16 v[76:79], v[140:143], v[182:185], v[76:79]
	v_mfma_f32_16x16x32_bf16 v[68:71], v[148:151], v[182:185], v[68:71]
	v_mfma_f32_16x16x32_bf16 v[60:63], v[140:143], v[190:193], v[60:63]
	v_mfma_f32_16x16x32_bf16 v[56:59], v[148:151], v[190:193], v[56:59]
	v_mfma_f32_16x16x32_bf16 v[52:55], v[140:143], v[210:213], v[52:55]
	v_mfma_f32_16x16x32_bf16 v[48:51], v[148:151], v[210:213], v[48:51]
	v_mfma_f32_16x16x32_bf16 v[44:47], v[140:143], v[244:247], v[44:47]
	v_mfma_f32_16x16x32_bf16 v[40:43], v[148:151], v[244:247], v[40:43]
	v_mfma_f32_16x16x32_bf16 v[36:39], v[152:155], v[178:181], v[36:39]
	v_mfma_f32_16x16x32_bf16 v[28:31], v[160:163], v[178:181], v[28:31]
	v_mfma_f32_16x16x32_bf16 v[24:27], v[152:155], v[186:189], v[24:27]
	v_mfma_f32_16x16x32_bf16 v[20:23], v[160:163], v[186:189], v[20:23]
	v_mfma_f32_16x16x32_bf16 v[16:19], v[152:155], v[194:197], v[16:19]
	v_mfma_f32_16x16x32_bf16 v[12:15], v[160:163], v[194:197], v[12:15]
	v_mfma_f32_16x16x32_bf16 v[6:9], v[152:155], v[240:243], v[8:11]
	v_mfma_f32_16x16x32_bf16 v[2:5], v[160:163], v[240:243], v[2:5]
	v_mfma_f32_16x16x32_bf16 v[36:39], v[156:159], v[182:185], v[36:39]
	v_mfma_f32_16x16x32_bf16 v[28:31], v[174:177], v[182:185], v[28:31]
	v_mfma_f32_16x16x32_bf16 v[24:27], v[156:159], v[190:193], v[24:27]
	v_mfma_f32_16x16x32_bf16 v[20:23], v[174:177], v[190:193], v[20:23]
	v_mfma_f32_16x16x32_bf16 v[16:19], v[156:159], v[210:213], v[16:19]
	v_mfma_f32_16x16x32_bf16 v[12:15], v[174:177], v[210:213], v[12:15]
	v_mfma_f32_16x16x32_bf16 v[8:11], v[156:159], v[244:247], v[6:9]
	v_mfma_f32_16x16x32_bf16 v[4:7], v[174:177], v[244:247], v[2:5]
	s_barrier
	s_add_i32 s56, s56, 2
	s_add_u32 s15, s15, 0x10000
	s_addc_u32 s51, s51, 0
	s_add_u32 s48, s48, 0x100
	s_addc_u32 s49, s49, 0
	s_cmp_gt_u32 s56, 29
	s_cbranch_scc0 .LBB0_788
	s_and_b64 vcc, exec, s[46:47]
	s_cbranch_vccz .LBB0_791
	s_barrier

.LBB0_877:
	s_add_u32 s62, s60, 0x100
	s_addc_u32 s63, s61, 0
	s_add_i32 s34, 0, 0x10000
	s_cmp_eq_u32 s49, 60
	s_cselect_b32 s67, s51, s63
	s_cselect_b32 s66, s50, s62
	s_cselect_b32 s65, s53, s28
	s_cselect_b32 s64, s52, s13
	s_add_i32 s55, 0, 0x14000
	ds_read_b128 v[132:135], v190 offset:0
	ds_read_b128 v[136:139], v190 offset:1024
	ds_read_b128 v[140:143], v190 offset:2048
	ds_read_b128 v[144:147], v190 offset:3072
	ds_read_b128 v[148:151], v190 offset:16384
	ds_read_b128 v[152:155], v190 offset:17408
	ds_read_b128 v[168:171], v190 offset:18432
	ds_read_b128 v[172:175], v190 offset:19456
	s_add_i32 m0, s29, 0xc000
	ds_read_b128 v[176:179], v189
	ds_read_b128 v[180:183], v189 offset:1024
	ds_read_b128 v[184:187], v189 offset:2048
	ds_read_b128 v[192:195], v189 offset:3072
	ds_read_b128 v[210:213], v189 offset:4096
	ds_read_b128 v[234:237], v189 offset:5120
	ds_read_b128 v[238:241], v189 offset:6144
	ds_read_b128 v[242:245], v189 offset:7168
	global_load_lds_dwordx4 v164, s[60:61]
	s_add_i32 m0, s29, 0xe000
	s_nop 0
	global_load_lds_dwordx4 v166, s[60:61]
	s_waitcnt vmcnt(8) lgkmcnt(0)
	s_barrier
	v_mfma_f32_16x16x32_bf16 v[128:131], v[132:135], v[176:179], v[128:131]
	v_mfma_f32_16x16x32_bf16 v[124:127], v[140:143], v[176:179], v[124:127]
	v_mfma_f32_16x16x32_bf16 v[112:115], v[132:135], v[184:187], v[112:115]
	v_mfma_f32_16x16x32_bf16 v[108:111], v[140:143], v[184:187], v[108:111]
	v_mfma_f32_16x16x32_bf16 v[96:99], v[132:135], v[210:213], v[96:99]
	v_mfma_f32_16x16x32_bf16 v[92:95], v[140:143], v[210:213], v[92:95]
	v_mfma_f32_16x16x32_bf16 v[80:83], v[132:135], v[238:241], v[80:83]
	v_mfma_f32_16x16x32_bf16 v[76:79], v[140:143], v[238:241], v[76:79]
	v_mfma_f32_16x16x32_bf16 v[128:131], v[136:139], v[180:183], v[128:131]
	v_mfma_f32_16x16x32_bf16 v[124:127], v[144:147], v[180:183], v[124:127]
	v_mfma_f32_16x16x32_bf16 v[112:115], v[136:139], v[192:195], v[112:115]
	v_mfma_f32_16x16x32_bf16 v[108:111], v[144:147], v[192:195], v[108:111]
	v_mfma_f32_16x16x32_bf16 v[96:99], v[136:139], v[234:237], v[96:99]
	v_mfma_f32_16x16x32_bf16 v[92:95], v[144:147], v[234:237], v[92:95]
	v_mfma_f32_16x16x32_bf16 v[80:83], v[136:139], v[242:245], v[80:83]
	v_mfma_f32_16x16x32_bf16 v[76:79], v[144:147], v[242:245], v[76:79]
	v_mfma_f32_16x16x32_bf16 v[120:123], v[148:151], v[176:179], v[120:123]
	v_mfma_f32_16x16x32_bf16 v[116:119], v[168:171], v[176:179], v[116:119]
	v_mfma_f32_16x16x32_bf16 v[104:107], v[148:151], v[184:187], v[104:107]
	v_mfma_f32_16x16x32_bf16 v[100:103], v[168:171], v[184:187], v[100:103]
	v_mfma_f32_16x16x32_bf16 v[88:91], v[148:151], v[210:213], v[88:91]
	v_mfma_f32_16x16x32_bf16 v[84:87], v[168:171], v[210:213], v[84:87]
	v_mfma_f32_16x16x32_bf16 v[72:75], v[148:151], v[238:241], v[72:75]
	v_mfma_f32_16x16x32_bf16 v[68:71], v[168:171], v[238:241], v[68:71]
	v_mfma_f32_16x16x32_bf16 v[120:123], v[152:155], v[180:183], v[120:123]
	v_mfma_f32_16x16x32_bf16 v[116:119], v[172:175], v[180:183], v[116:119]
	v_mfma_f32_16x16x32_bf16 v[104:107], v[152:155], v[192:195], v[104:107]
	v_mfma_f32_16x16x32_bf16 v[100:103], v[172:175], v[192:195], v[100:103]
	v_mfma_f32_16x16x32_bf16 v[88:91], v[152:155], v[234:237], v[88:91]
	v_mfma_f32_16x16x32_bf16 v[84:87], v[172:175], v[234:237], v[84:87]
	v_mfma_f32_16x16x32_bf16 v[72:75], v[152:155], v[242:245], v[72:75]
	v_mfma_f32_16x16x32_bf16 v[68:71], v[172:175], v[242:245], v[68:71]
	s_barrier
	s_add_i32 s34, s34, s0
	s_mov_b32 m0, s34
	ds_read_b128 v[176:179], v189 offset:16384
	ds_read_b128 v[180:183], v189 offset:17408
	ds_read_b128 v[184:187], v189 offset:18432
	ds_read_b128 v[192:195], v189 offset:19456
	ds_read_b128 v[210:213], v189 offset:20480
	ds_read_b128 v[234:237], v189 offset:21504
	ds_read_b128 v[238:241], v189 offset:22528
	ds_read_b128 v[242:245], v189 offset:23552
	global_load_lds_dwordx4 v156, s[64:65]
	s_add_i32 m0, s34, 0x2000
	s_add_u32 s34, s64, 0x4000
	s_addc_u32 s35, s65, 0
	s_add_i32 s55, s55, s0
	global_load_lds_dwordx4 v160, s[64:65]
	s_mov_b32 m0, s55
	s_nop 0
	global_load_lds_dwordx4 v156, s[34:35]
	s_add_i32 m0, s55, 0x2000
	s_nop 0
	global_load_lds_dwordx4 v160, s[34:35]
	s_mov_b32 m0, s29
	s_nop 0
	global_load_lds_dwordx4 v158, s[66:67]
	s_waitcnt vmcnt(7) lgkmcnt(0)
	s_barrier
	v_mfma_f32_16x16x32_bf16 v[64:67], v[132:135], v[176:179], v[64:67]
	v_mfma_f32_16x16x32_bf16 v[60:63], v[140:143], v[176:179], v[60:63]
	v_mfma_f32_16x16x32_bf16 v[48:51], v[132:135], v[184:187], v[48:51]
	v_mfma_f32_16x16x32_bf16 v[44:47], v[140:143], v[184:187], v[44:47]
	v_mfma_f32_16x16x32_bf16 v[30:33], v[132:135], v[210:213], v[30:33]
	v_mfma_f32_16x16x32_bf16 v[26:29], v[140:143], v[210:213], v[26:29]
	v_mfma_f32_16x16x32_bf16 v[14:17], v[132:135], v[238:241], v[14:17]
	v_mfma_f32_16x16x32_bf16 v[10:13], v[140:143], v[238:241], v[10:13]
	v_mfma_f32_16x16x32_bf16 v[64:67], v[136:139], v[180:183], v[64:67]
	v_mfma_f32_16x16x32_bf16 v[60:63], v[144:147], v[180:183], v[60:63]
	v_mfma_f32_16x16x32_bf16 v[48:51], v[136:139], v[192:195], v[48:51]
	v_mfma_f32_16x16x32_bf16 v[44:47], v[144:147], v[192:195], v[44:47]
	v_mfma_f32_16x16x32_bf16 v[30:33], v[136:139], v[234:237], v[30:33]
	v_mfma_f32_16x16x32_bf16 v[26:29], v[144:147], v[234:237], v[26:29]
	v_mfma_f32_16x16x32_bf16 v[14:17], v[136:139], v[242:245], v[14:17]
	v_mfma_f32_16x16x32_bf16 v[10:13], v[144:147], v[242:245], v[10:13]
	v_mfma_f32_16x16x32_bf16 v[56:59], v[148:151], v[176:179], v[56:59]
	v_mfma_f32_16x16x32_bf16 v[52:55], v[168:171], v[176:179], v[52:55]
	v_mfma_f32_16x16x32_bf16 v[40:43], v[148:151], v[184:187], v[40:43]
	v_mfma_f32_16x16x32_bf16 v[36:39], v[168:171], v[184:187], v[36:39]
	v_mfma_f32_16x16x32_bf16 v[22:25], v[148:151], v[210:213], v[22:25]
	v_mfma_f32_16x16x32_bf16 v[18:21], v[168:171], v[210:213], v[18:21]
	v_mfma_f32_16x16x32_bf16 v[6:9], v[148:151], v[238:241], v[6:9]
	v_mfma_f32_16x16x32_bf16 v[2:5], v[168:171], v[238:241], v[2:5]
	v_mfma_f32_16x16x32_bf16 v[56:59], v[152:155], v[180:183], v[56:59]
	v_mfma_f32_16x16x32_bf16 v[52:55], v[172:175], v[180:183], v[52:55]
	v_mfma_f32_16x16x32_bf16 v[40:43], v[152:155], v[192:195], v[40:43]
	v_mfma_f32_16x16x32_bf16 v[36:39], v[172:175], v[192:195], v[36:39]
	v_mfma_f32_16x16x32_bf16 v[22:25], v[152:155], v[234:237], v[22:25]
	v_mfma_f32_16x16x32_bf16 v[18:21], v[172:175], v[234:237], v[18:21]
	v_mfma_f32_16x16x32_bf16 v[6:9], v[152:155], v[242:245], v[6:9]
	v_mfma_f32_16x16x32_bf16 v[2:5], v[172:175], v[242:245], v[2:5]
	s_barrier
	s_mov_b32 m0, s45
	s_nop 0
	global_load_lds_dwordx4 v162, s[66:67]
	s_add_i32 s55, 0, 0x18000
	s_add_i32 s58, 0, 0x1c000
	ds_read_b128 v[132:135], v190 offset:32768
	ds_read_b128 v[136:139], v190 offset:33792
	ds_read_b128 v[140:143], v190 offset:34816
	ds_read_b128 v[144:147], v190 offset:35840
	ds_read_b128 v[148:151], v190 offset:49152
	ds_read_b128 v[152:155], v190 offset:50176
	ds_read_b128 v[168:171], v190 offset:51200
	ds_read_b128 v[172:175], v190 offset:52224
	s_add_u32 s34, s66, 0x100000
	s_addc_u32 s35, s67, 0
	s_mov_b32 m0, s82
	ds_read_b128 v[176:179], v189 offset:32768
	ds_read_b128 v[180:183], v189 offset:33792
	ds_read_b128 v[184:187], v189 offset:34816
	ds_read_b128 v[192:195], v189 offset:35840
	ds_read_b128 v[210:213], v189 offset:36864
	ds_read_b128 v[234:237], v189 offset:37888
	ds_read_b128 v[238:241], v189 offset:38912
	ds_read_b128 v[242:245], v189 offset:39936
	global_load_lds_dwordx4 v158, s[34:35]
	s_mov_b32 m0, s90
	s_nop 0
	global_load_lds_dwordx4 v162, s[34:35]
	s_waitcnt vmcnt(8) lgkmcnt(0)
	s_barrier
	v_mfma_f32_16x16x32_bf16 v[128:131], v[132:135], v[176:179], v[128:131]
	v_mfma_f32_16x16x32_bf16 v[124:127], v[140:143], v[176:179], v[124:127]
	v_mfma_f32_16x16x32_bf16 v[112:115], v[132:135], v[184:187], v[112:115]
	v_mfma_f32_16x16x32_bf16 v[108:111], v[140:143], v[184:187], v[108:111]
	v_mfma_f32_16x16x32_bf16 v[96:99], v[132:135], v[210:213], v[96:99]
	v_mfma_f32_16x16x32_bf16 v[92:95], v[140:143], v[210:213], v[92:95]
	v_mfma_f32_16x16x32_bf16 v[80:83], v[132:135], v[238:241], v[80:83]
	v_mfma_f32_16x16x32_bf16 v[76:79], v[140:143], v[238:241], v[76:79]
	v_mfma_f32_16x16x32_bf16 v[128:131], v[136:139], v[180:183], v[128:131]
	v_mfma_f32_16x16x32_bf16 v[124:127], v[144:147], v[180:183], v[124:127]
	v_mfma_f32_16x16x32_bf16 v[112:115], v[136:139], v[192:195], v[112:115]
	v_mfma_f32_16x16x32_bf16 v[108:111], v[144:147], v[192:195], v[108:111]
	v_mfma_f32_16x16x32_bf16 v[96:99], v[136:139], v[234:237], v[96:99]
	v_mfma_f32_16x16x32_bf16 v[92:95], v[144:147], v[234:237], v[92:95]
	v_mfma_f32_16x16x32_bf16 v[80:83], v[136:139], v[242:245], v[80:83]
	v_mfma_f32_16x16x32_bf16 v[76:79], v[144:147], v[242:245], v[76:79]
	v_mfma_f32_16x16x32_bf16 v[120:123], v[148:151], v[176:179], v[120:123]
	v_mfma_f32_16x16x32_bf16 v[116:119], v[168:171], v[176:179], v[116:119]
	v_mfma_f32_16x16x32_bf16 v[104:107], v[148:151], v[184:187], v[104:107]
	v_mfma_f32_16x16x32_bf16 v[100:103], v[168:171], v[184:187], v[100:103]
	v_mfma_f32_16x16x32_bf16 v[88:91], v[148:151], v[210:213], v[88:91]
	v_mfma_f32_16x16x32_bf16 v[84:87], v[168:171], v[210:213], v[84:87]
	v_mfma_f32_16x16x32_bf16 v[72:75], v[148:151], v[238:241], v[72:75]
	v_mfma_f32_16x16x32_bf16 v[68:71], v[168:171], v[238:241], v[68:71]
	v_mfma_f32_16x16x32_bf16 v[120:123], v[152:155], v[180:183], v[120:123]
	v_mfma_f32_16x16x32_bf16 v[116:119], v[172:175], v[180:183], v[116:119]
	v_mfma_f32_16x16x32_bf16 v[104:107], v[152:155], v[192:195], v[104:107]
	v_mfma_f32_16x16x32_bf16 v[100:103], v[172:175], v[192:195], v[100:103]
	v_mfma_f32_16x16x32_bf16 v[88:91], v[152:155], v[234:237], v[88:91]
	v_mfma_f32_16x16x32_bf16 v[84:87], v[172:175], v[234:237], v[84:87]
	v_mfma_f32_16x16x32_bf16 v[72:75], v[152:155], v[242:245], v[72:75]
	v_mfma_f32_16x16x32_bf16 v[68:71], v[172:175], v[242:245], v[68:71]
	s_barrier
	s_add_u32 s34, s64, 0x8000
	s_addc_u32 s35, s65, 0
	s_add_i32 s55, s55, s0
	s_mov_b32 m0, s55
	ds_read_b128 v[176:179], v189 offset:49152
	ds_read_b128 v[180:183], v189 offset:50176
	ds_read_b128 v[184:187], v189 offset:51200
	ds_read_b128 v[192:195], v189 offset:52224
	ds_read_b128 v[210:213], v189 offset:53248
	ds_read_b128 v[234:237], v189 offset:54272
	ds_read_b128 v[238:241], v189 offset:55296
	ds_read_b128 v[242:245], v189 offset:56320
	global_load_lds_dwordx4 v156, s[34:35]
	s_add_i32 m0, s55, 0x2000
	s_mov_b64 s[100:101], s[34:35]
	s_add_u32 s34, s64, 0xc000
	s_addc_u32 s35, s65, 0
	s_add_i32 s55, s58, s0
	global_load_lds_dwordx4 v160, s[100:101]
	s_mov_b32 m0, s55
	s_nop 0
	global_load_lds_dwordx4 v156, s[34:35]
	s_add_i32 m0, s55, 0x2000
	s_nop 0
	global_load_lds_dwordx4 v160, s[34:35]
	s_mov_b32 m0, s91
	s_nop 0
	s_add_u32 s100, s66, s92
	s_addc_u32 s101, s67, s93
	global_load_lds_dwordx4 v158, s[100:101]
	s_mov_b32 m0, s30
	s_nop 0
	s_add_u32 s100, s66, s92
	s_addc_u32 s101, s67, s93
	global_load_lds_dwordx4 v162, s[100:101]
	s_waitcnt vmcnt(8) lgkmcnt(0)
	s_barrier
	v_mfma_f32_16x16x32_bf16 v[64:67], v[132:135], v[176:179], v[64:67]
	v_mfma_f32_16x16x32_bf16 v[60:63], v[140:143], v[176:179], v[60:63]
	v_mfma_f32_16x16x32_bf16 v[48:51], v[132:135], v[184:187], v[48:51]
	v_mfma_f32_16x16x32_bf16 v[44:47], v[140:143], v[184:187], v[44:47]
	v_mfma_f32_16x16x32_bf16 v[30:33], v[132:135], v[210:213], v[30:33]
	v_mfma_f32_16x16x32_bf16 v[26:29], v[140:143], v[210:213], v[26:29]
	v_mfma_f32_16x16x32_bf16 v[14:17], v[132:135], v[238:241], v[14:17]
	v_mfma_f32_16x16x32_bf16 v[10:13], v[140:143], v[238:241], v[10:13]
	v_mfma_f32_16x16x32_bf16 v[64:67], v[136:139], v[180:183], v[64:67]
	v_mfma_f32_16x16x32_bf16 v[60:63], v[144:147], v[180:183], v[60:63]
	v_mfma_f32_16x16x32_bf16 v[48:51], v[136:139], v[192:195], v[48:51]
	v_mfma_f32_16x16x32_bf16 v[44:47], v[144:147], v[192:195], v[44:47]
	v_mfma_f32_16x16x32_bf16 v[30:33], v[136:139], v[234:237], v[30:33]
	v_mfma_f32_16x16x32_bf16 v[26:29], v[144:147], v[234:237], v[26:29]
	v_mfma_f32_16x16x32_bf16 v[14:17], v[136:139], v[242:245], v[14:17]
	v_mfma_f32_16x16x32_bf16 v[10:13], v[144:147], v[242:245], v[10:13]
	v_mfma_f32_16x16x32_bf16 v[56:59], v[148:151], v[176:179], v[56:59]
	v_mfma_f32_16x16x32_bf16 v[52:55], v[168:171], v[176:179], v[52:55]
	v_mfma_f32_16x16x32_bf16 v[40:43], v[148:151], v[184:187], v[40:43]
	v_mfma_f32_16x16x32_bf16 v[36:39], v[168:171], v[184:187], v[36:39]
	v_mfma_f32_16x16x32_bf16 v[22:25], v[148:151], v[210:213], v[22:25]
	v_mfma_f32_16x16x32_bf16 v[18:21], v[168:171], v[210:213], v[18:21]
	v_mfma_f32_16x16x32_bf16 v[6:9], v[148:151], v[238:241], v[6:9]
	v_mfma_f32_16x16x32_bf16 v[2:5], v[168:171], v[238:241], v[2:5]
	v_mfma_f32_16x16x32_bf16 v[56:59], v[152:155], v[180:183], v[56:59]
	v_mfma_f32_16x16x32_bf16 v[52:55], v[172:175], v[180:183], v[52:55]
	v_mfma_f32_16x16x32_bf16 v[40:43], v[152:155], v[192:195], v[40:43]
	v_mfma_f32_16x16x32_bf16 v[36:39], v[172:175], v[192:195], v[36:39]
	v_mfma_f32_16x16x32_bf16 v[22:25], v[152:155], v[234:237], v[22:25]
	v_mfma_f32_16x16x32_bf16 v[18:21], v[172:175], v[234:237], v[18:21]
	v_mfma_f32_16x16x32_bf16 v[6:9], v[152:155], v[242:245], v[6:9]
	v_mfma_f32_16x16x32_bf16 v[2:5], v[172:175], v[242:245], v[2:5]
	s_barrier
	s_add_i32 s49, s49, 2
	s_add_u32 s13, s13, 0x10000
	s_addc_u32 s28, s28, 0
	s_cmp_gt_u32 s49, 61
	s_mov_b64 s[60:61], s[62:63]
	s_cbranch_scc0 .LBB0_877
	s_and_b64 vcc, exec, s[46:47]
	s_cbranch_vccz .LBB0_880
	s_barrier

.LBB0_1070:
	s_add_u32 s34, s12, 0xfff00080
	s_addc_u32 s35, s13, -1
	s_add_i32 s48, 0, 0x10000
	s_cmp_eq_u32 s59, 28
	s_cselect_b32 s67, s61, s35
	s_cselect_b32 s66, s60, s34
	s_cselect_b32 s65, s63, s58
	s_cselect_b32 s64, s62, s28
	s_add_i32 s49, 0, 0x14000
	ds_read_b128 v[100:103], v2 offset:0
	ds_read_b128 v[112:115], v2 offset:1024
	ds_read_b128 v[172:175], v2 offset:2048
	ds_read_b128 v[188:191], v2 offset:3072
	ds_read_b128 v[192:195], v2 offset:16384
	ds_read_b128 v[200:203], v2 offset:17408
	ds_read_b128 v[204:207], v2 offset:18432
	ds_read_b128 v[210:213], v2 offset:19456
	s_add_i32 m0, s29, 0xc000
	ds_read_b128 v[216:219], v197
	ds_read_b128 v[220:223], v197 offset:1024
	ds_read_b128 v[224:227], v197 offset:2048
	ds_read_b128 v[228:231], v197 offset:3072
	ds_read_b128 v[232:235], v197 offset:4096
	ds_read_b128 v[236:239], v197 offset:5120
	ds_read_b128 v[240:243], v197 offset:6144
	ds_read_b128 v[244:247], v197 offset:7168
	global_load_lds_dwordx4 v184, s[12:13]
	s_add_i32 m0, s29, 0xe000
	s_nop 0
	global_load_lds_dwordx4 v186, s[12:13]
	s_waitcnt vmcnt(8) lgkmcnt(0)
	s_barrier
	v_mfma_i32_16x16x64_i8 v[168:171], v[100:103], v[216:219], v[168:171]
	v_mfma_i32_16x16x64_i8 v[160:163], v[172:175], v[216:219], v[160:163]
	v_mfma_i32_16x16x64_i8 v[152:155], v[100:103], v[224:227], v[152:155]
	v_mfma_i32_16x16x64_i8 v[144:147], v[172:175], v[224:227], v[144:147]
	v_mfma_i32_16x16x64_i8 v[136:139], v[100:103], v[232:235], v[136:139]
	v_mfma_i32_16x16x64_i8 v[128:131], v[172:175], v[232:235], v[128:131]
	v_mfma_i32_16x16x64_i8 v[120:123], v[100:103], v[240:243], v[120:123]
	v_mfma_i32_16x16x64_i8 v[108:111], v[172:175], v[240:243], v[108:111]
	v_mfma_i32_16x16x64_i8 v[168:171], v[112:115], v[220:223], v[168:171]
	v_mfma_i32_16x16x64_i8 v[160:163], v[188:191], v[220:223], v[160:163]
	v_mfma_i32_16x16x64_i8 v[152:155], v[112:115], v[228:231], v[152:155]
	v_mfma_i32_16x16x64_i8 v[144:147], v[188:191], v[228:231], v[144:147]
	v_mfma_i32_16x16x64_i8 v[136:139], v[112:115], v[236:239], v[136:139]
	v_mfma_i32_16x16x64_i8 v[128:131], v[188:191], v[236:239], v[128:131]
	v_mfma_i32_16x16x64_i8 v[120:123], v[112:115], v[244:247], v[120:123]
	v_mfma_i32_16x16x64_i8 v[108:111], v[188:191], v[244:247], v[108:111]
	v_mfma_i32_16x16x64_i8 v[164:167], v[192:195], v[216:219], v[164:167]
	v_mfma_i32_16x16x64_i8 v[156:159], v[204:207], v[216:219], v[156:159]
	v_mfma_i32_16x16x64_i8 v[148:151], v[192:195], v[224:227], v[148:151]
	v_mfma_i32_16x16x64_i8 v[140:143], v[204:207], v[224:227], v[140:143]
	v_mfma_i32_16x16x64_i8 v[132:135], v[192:195], v[232:235], v[132:135]
	v_mfma_i32_16x16x64_i8 v[124:127], v[204:207], v[232:235], v[124:127]
	v_mfma_i32_16x16x64_i8 v[116:119], v[192:195], v[240:243], v[116:119]
	v_mfma_i32_16x16x64_i8 v[104:107], v[204:207], v[240:243], v[104:107]
	v_mfma_i32_16x16x64_i8 v[164:167], v[200:203], v[220:223], v[164:167]
	v_mfma_i32_16x16x64_i8 v[156:159], v[210:213], v[220:223], v[156:159]
	v_mfma_i32_16x16x64_i8 v[148:151], v[200:203], v[228:231], v[148:151]
	v_mfma_i32_16x16x64_i8 v[140:143], v[210:213], v[228:231], v[140:143]
	v_mfma_i32_16x16x64_i8 v[132:135], v[200:203], v[236:239], v[132:135]
	v_mfma_i32_16x16x64_i8 v[124:127], v[210:213], v[236:239], v[124:127]
	v_mfma_i32_16x16x64_i8 v[116:119], v[200:203], v[244:247], v[116:119]
	v_mfma_i32_16x16x64_i8 v[104:107], v[210:213], v[244:247], v[104:107]
	s_barrier
	s_add_i32 s34, s48, s0
	s_mov_b32 m0, s34
	ds_read_b128 v[216:219], v197 offset:16384
	ds_read_b128 v[220:223], v197 offset:17408
	ds_read_b128 v[224:227], v197 offset:18432
	ds_read_b128 v[228:231], v197 offset:19456
	ds_read_b128 v[232:235], v197 offset:20480
	ds_read_b128 v[236:239], v197 offset:21504
	ds_read_b128 v[240:243], v197 offset:22528
	ds_read_b128 v[244:247], v197 offset:23552
	global_load_lds_dwordx4 v176, s[64:65]
	s_add_i32 m0, s34, 0x2000
	s_add_u32 s34, s64, 0x4000
	s_addc_u32 s35, s65, 0
	s_add_i32 s48, s49, s0
	global_load_lds_dwordx4 v180, s[64:65]
	s_mov_b32 m0, s48
	s_nop 0
	global_load_lds_dwordx4 v176, s[34:35]
	s_add_i32 m0, s48, 0x2000
	s_nop 0
	global_load_lds_dwordx4 v180, s[34:35]
	s_mov_b32 m0, s29
	s_nop 0
	global_load_lds_dwordx4 v178, s[66:67]
	s_waitcnt vmcnt(7) lgkmcnt(0)
	s_barrier
	v_mfma_i32_16x16x64_i8 v[96:99], v[100:103], v[216:219], v[96:99]
	v_mfma_i32_16x16x64_i8 v[88:91], v[172:175], v[216:219], v[88:91]
	v_mfma_i32_16x16x64_i8 v[80:83], v[100:103], v[224:227], v[80:83]
	v_mfma_i32_16x16x64_i8 v[72:75], v[172:175], v[224:227], v[72:75]
	v_mfma_i32_16x16x64_i8 v[64:67], v[100:103], v[232:235], v[64:67]
	v_mfma_i32_16x16x64_i8 v[56:59], v[172:175], v[232:235], v[56:59]
	v_mfma_i32_16x16x64_i8 v[48:51], v[100:103], v[240:243], v[48:51]
	v_mfma_i32_16x16x64_i8 v[40:43], v[172:175], v[240:243], v[40:43]
	v_mfma_i32_16x16x64_i8 v[96:99], v[112:115], v[220:223], v[96:99]
	v_mfma_i32_16x16x64_i8 v[88:91], v[188:191], v[220:223], v[88:91]
	v_mfma_i32_16x16x64_i8 v[80:83], v[112:115], v[228:231], v[80:83]
	v_mfma_i32_16x16x64_i8 v[72:75], v[188:191], v[228:231], v[72:75]
	v_mfma_i32_16x16x64_i8 v[64:67], v[112:115], v[236:239], v[64:67]
	v_mfma_i32_16x16x64_i8 v[56:59], v[188:191], v[236:239], v[56:59]
	v_mfma_i32_16x16x64_i8 v[48:51], v[112:115], v[244:247], v[48:51]
	v_mfma_i32_16x16x64_i8 v[40:43], v[188:191], v[244:247], v[40:43]
	v_mfma_i32_16x16x64_i8 v[92:95], v[192:195], v[216:219], v[92:95]
	v_mfma_i32_16x16x64_i8 v[84:87], v[204:207], v[216:219], v[84:87]
	v_mfma_i32_16x16x64_i8 v[76:79], v[192:195], v[224:227], v[76:79]
	v_mfma_i32_16x16x64_i8 v[68:71], v[204:207], v[224:227], v[68:71]
	v_mfma_i32_16x16x64_i8 v[60:63], v[192:195], v[232:235], v[60:63]
	v_mfma_i32_16x16x64_i8 v[52:55], v[204:207], v[232:235], v[52:55]
	v_mfma_i32_16x16x64_i8 v[44:47], v[192:195], v[240:243], v[44:47]
	v_mfma_i32_16x16x64_i8 v[36:39], v[204:207], v[240:243], v[36:39]
	v_mfma_i32_16x16x64_i8 v[92:95], v[200:203], v[220:223], v[92:95]
	v_mfma_i32_16x16x64_i8 v[84:87], v[210:213], v[220:223], v[84:87]
	v_mfma_i32_16x16x64_i8 v[76:79], v[200:203], v[228:231], v[76:79]
	v_mfma_i32_16x16x64_i8 v[68:71], v[210:213], v[228:231], v[68:71]
	v_mfma_i32_16x16x64_i8 v[60:63], v[200:203], v[236:239], v[60:63]
	v_mfma_i32_16x16x64_i8 v[52:55], v[210:213], v[236:239], v[52:55]
	v_mfma_i32_16x16x64_i8 v[44:47], v[200:203], v[244:247], v[44:47]
	v_mfma_i32_16x16x64_i8 v[36:39], v[210:213], v[244:247], v[36:39]
	s_barrier
	s_mov_b32 m0, s45
	s_nop 0
	global_load_lds_dwordx4 v182, s[66:67]
	s_add_i32 s48, 0, 0x18000
	s_add_i32 s49, 0, 0x1c000
	ds_read_b128 v[100:103], v2 offset:32768
	ds_read_b128 v[112:115], v2 offset:33792
	ds_read_b128 v[172:175], v2 offset:34816
	ds_read_b128 v[188:191], v2 offset:35840
	ds_read_b128 v[192:195], v2 offset:49152
	ds_read_b128 v[200:203], v2 offset:50176
	ds_read_b128 v[204:207], v2 offset:51200
	ds_read_b128 v[210:213], v2 offset:52224
	s_add_u32 s34, s66, 0x100000
	s_addc_u32 s35, s67, 0
	s_mov_b32 m0, s82
	ds_read_b128 v[216:219], v197 offset:32768
	ds_read_b128 v[220:223], v197 offset:33792
	ds_read_b128 v[224:227], v197 offset:34816
	ds_read_b128 v[228:231], v197 offset:35840
	ds_read_b128 v[232:235], v197 offset:36864
	ds_read_b128 v[236:239], v197 offset:37888
	ds_read_b128 v[240:243], v197 offset:38912
	ds_read_b128 v[244:247], v197 offset:39936
	global_load_lds_dwordx4 v178, s[34:35]
	s_mov_b32 m0, s90
	s_nop 0
	global_load_lds_dwordx4 v182, s[34:35]
	s_waitcnt vmcnt(8) lgkmcnt(0)
	s_barrier
	v_mfma_i32_16x16x64_i8 v[168:171], v[100:103], v[216:219], v[168:171]
	v_mfma_i32_16x16x64_i8 v[160:163], v[172:175], v[216:219], v[160:163]
	v_mfma_i32_16x16x64_i8 v[152:155], v[100:103], v[224:227], v[152:155]
	v_mfma_i32_16x16x64_i8 v[144:147], v[172:175], v[224:227], v[144:147]
	v_mfma_i32_16x16x64_i8 v[136:139], v[100:103], v[232:235], v[136:139]
	v_mfma_i32_16x16x64_i8 v[128:131], v[172:175], v[232:235], v[128:131]
	v_mfma_i32_16x16x64_i8 v[120:123], v[100:103], v[240:243], v[120:123]
	v_mfma_i32_16x16x64_i8 v[108:111], v[172:175], v[240:243], v[108:111]
	v_mfma_i32_16x16x64_i8 v[168:171], v[112:115], v[220:223], v[168:171]
	v_mfma_i32_16x16x64_i8 v[160:163], v[188:191], v[220:223], v[160:163]
	v_mfma_i32_16x16x64_i8 v[152:155], v[112:115], v[228:231], v[152:155]
	v_mfma_i32_16x16x64_i8 v[144:147], v[188:191], v[228:231], v[144:147]
	v_mfma_i32_16x16x64_i8 v[136:139], v[112:115], v[236:239], v[136:139]
	v_mfma_i32_16x16x64_i8 v[128:131], v[188:191], v[236:239], v[128:131]
	v_mfma_i32_16x16x64_i8 v[120:123], v[112:115], v[244:247], v[120:123]
	v_mfma_i32_16x16x64_i8 v[108:111], v[188:191], v[244:247], v[108:111]
	v_mfma_i32_16x16x64_i8 v[164:167], v[192:195], v[216:219], v[164:167]
	v_mfma_i32_16x16x64_i8 v[156:159], v[204:207], v[216:219], v[156:159]
	v_mfma_i32_16x16x64_i8 v[148:151], v[192:195], v[224:227], v[148:151]
	v_mfma_i32_16x16x64_i8 v[140:143], v[204:207], v[224:227], v[140:143]
	v_mfma_i32_16x16x64_i8 v[132:135], v[192:195], v[232:235], v[132:135]
	v_mfma_i32_16x16x64_i8 v[124:127], v[204:207], v[232:235], v[124:127]
	v_mfma_i32_16x16x64_i8 v[116:119], v[192:195], v[240:243], v[116:119]
	v_mfma_i32_16x16x64_i8 v[104:107], v[204:207], v[240:243], v[104:107]
	v_mfma_i32_16x16x64_i8 v[164:167], v[200:203], v[220:223], v[164:167]
	v_mfma_i32_16x16x64_i8 v[156:159], v[210:213], v[220:223], v[156:159]
	v_mfma_i32_16x16x64_i8 v[148:151], v[200:203], v[228:231], v[148:151]
	v_mfma_i32_16x16x64_i8 v[140:143], v[210:213], v[228:231], v[140:143]
	v_mfma_i32_16x16x64_i8 v[132:135], v[200:203], v[236:239], v[132:135]
	v_mfma_i32_16x16x64_i8 v[124:127], v[210:213], v[236:239], v[124:127]
	v_mfma_i32_16x16x64_i8 v[116:119], v[200:203], v[244:247], v[116:119]
	v_mfma_i32_16x16x64_i8 v[104:107], v[210:213], v[244:247], v[104:107]
	s_barrier
	s_add_u32 s34, s64, 0x8000
	s_addc_u32 s35, s65, 0
	s_add_i32 s48, s48, s0
	s_mov_b32 m0, s48
	ds_read_b128 v[216:219], v197 offset:49152
	ds_read_b128 v[220:223], v197 offset:50176
	ds_read_b128 v[224:227], v197 offset:51200
	ds_read_b128 v[228:231], v197 offset:52224
	ds_read_b128 v[232:235], v197 offset:53248
	ds_read_b128 v[236:239], v197 offset:54272
	ds_read_b128 v[240:243], v197 offset:55296
	ds_read_b128 v[244:247], v197 offset:56320
	global_load_lds_dwordx4 v176, s[34:35]
	s_add_i32 m0, s48, 0x2000
	s_mov_b64 s[100:101], s[34:35]
	s_add_u32 s34, s64, 0xc000
	s_addc_u32 s35, s65, 0
	s_add_i32 s48, s49, s0
	global_load_lds_dwordx4 v180, s[100:101]
	s_mov_b32 m0, s48
	s_nop 0
	global_load_lds_dwordx4 v176, s[34:35]
	s_add_i32 m0, s48, 0x2000
	s_nop 0
	global_load_lds_dwordx4 v180, s[34:35]
	s_mov_b32 m0, s91
	s_nop 0
	s_add_u32 s100, s66, s92
	s_addc_u32 s101, s67, s93
	global_load_lds_dwordx4 v178, s[100:101]
	s_mov_b32 m0, s30
	s_nop 0
	s_add_u32 s100, s66, s92
	s_addc_u32 s101, s67, s93
	global_load_lds_dwordx4 v182, s[100:101]
	s_waitcnt vmcnt(8) lgkmcnt(0)
	s_barrier
	v_mfma_i32_16x16x64_i8 v[96:99], v[100:103], v[216:219], v[96:99]
	v_mfma_i32_16x16x64_i8 v[88:91], v[172:175], v[216:219], v[88:91]
	v_mfma_i32_16x16x64_i8 v[80:83], v[100:103], v[224:227], v[80:83]
	v_mfma_i32_16x16x64_i8 v[72:75], v[172:175], v[224:227], v[72:75]
	v_mfma_i32_16x16x64_i8 v[64:67], v[100:103], v[232:235], v[64:67]
	v_mfma_i32_16x16x64_i8 v[56:59], v[172:175], v[232:235], v[56:59]
	v_mfma_i32_16x16x64_i8 v[48:51], v[100:103], v[240:243], v[48:51]
	v_mfma_i32_16x16x64_i8 v[40:43], v[172:175], v[240:243], v[40:43]
	v_mfma_i32_16x16x64_i8 v[96:99], v[112:115], v[220:223], v[96:99]
	v_mfma_i32_16x16x64_i8 v[88:91], v[188:191], v[220:223], v[88:91]
	v_mfma_i32_16x16x64_i8 v[80:83], v[112:115], v[228:231], v[80:83]
	v_mfma_i32_16x16x64_i8 v[72:75], v[188:191], v[228:231], v[72:75]
	v_mfma_i32_16x16x64_i8 v[64:67], v[112:115], v[236:239], v[64:67]
	v_mfma_i32_16x16x64_i8 v[56:59], v[188:191], v[236:239], v[56:59]
	v_mfma_i32_16x16x64_i8 v[48:51], v[112:115], v[244:247], v[48:51]
	v_mfma_i32_16x16x64_i8 v[40:43], v[188:191], v[244:247], v[40:43]
	v_mfma_i32_16x16x64_i8 v[92:95], v[192:195], v[216:219], v[92:95]
	v_mfma_i32_16x16x64_i8 v[84:87], v[204:207], v[216:219], v[84:87]
	v_mfma_i32_16x16x64_i8 v[76:79], v[192:195], v[224:227], v[76:79]
	v_mfma_i32_16x16x64_i8 v[68:71], v[204:207], v[224:227], v[68:71]
	v_mfma_i32_16x16x64_i8 v[60:63], v[192:195], v[232:235], v[60:63]
	v_mfma_i32_16x16x64_i8 v[52:55], v[204:207], v[232:235], v[52:55]
	v_mfma_i32_16x16x64_i8 v[44:47], v[192:195], v[240:243], v[44:47]
	v_mfma_i32_16x16x64_i8 v[36:39], v[204:207], v[240:243], v[36:39]
	v_mfma_i32_16x16x64_i8 v[92:95], v[200:203], v[220:223], v[92:95]
	v_mfma_i32_16x16x64_i8 v[84:87], v[210:213], v[220:223], v[84:87]
	v_mfma_i32_16x16x64_i8 v[76:79], v[200:203], v[228:231], v[76:79]
	v_mfma_i32_16x16x64_i8 v[68:71], v[210:213], v[228:231], v[68:71]
	v_mfma_i32_16x16x64_i8 v[60:63], v[200:203], v[236:239], v[60:63]
	v_mfma_i32_16x16x64_i8 v[52:55], v[210:213], v[236:239], v[52:55]
	v_mfma_i32_16x16x64_i8 v[44:47], v[200:203], v[244:247], v[44:47]
	v_mfma_i32_16x16x64_i8 v[36:39], v[210:213], v[244:247], v[36:39]
	s_barrier
	s_add_i32 s59, s59, 2
	s_add_u32 s28, s28, 0x10000
	s_addc_u32 s58, s58, 0
	s_add_u32 s12, s12, 0x100
	s_addc_u32 s13, s13, 0
	s_cmp_gt_u32 s59, 29
	s_cbranch_scc0 .LBB0_1070
	s_and_b64 vcc, exec, s[46:47]
	s_cbranch_vccz .LBB0_1073
	s_barrier

.LBB0_1261:
	s_add_u32 s42, s22, 0x100
	s_addc_u32 s43, s23, 0
	s_add_i32 s34, 0, 0x10000
	s_cmpk_eq_i32 s60, 0xa8
	s_cselect_b32 s51, s19, s43
	s_cselect_b32 s50, s18, s42
	s_cselect_b32 s49, s21, s59
	s_cselect_b32 s48, s20, s58
	s_add_i32 s35, 0, 0x14000
	ds_read_b128 v[132:135], v188 offset:0
	ds_read_b128 v[136:139], v188 offset:1024
	ds_read_b128 v[140:143], v188 offset:2048
	ds_read_b128 v[144:147], v188 offset:3072
	ds_read_b128 v[148:151], v188 offset:16384
	ds_read_b128 v[152:155], v188 offset:17408
	ds_read_b128 v[168:171], v188 offset:18432
	ds_read_b128 v[172:175], v188 offset:19456
	s_add_i32 m0, s29, 0xc000
	ds_read_b128 v[176:179], v187
	ds_read_b128 v[180:183], v187 offset:1024
	ds_read_b128 v[192:195], v187 offset:2048
	ds_read_b128 v[210:213], v187 offset:3072
	ds_read_b128 v[232:235], v187 offset:4096
	ds_read_b128 v[236:239], v187 offset:5120
	ds_read_b128 v[240:243], v187 offset:6144
	ds_read_b128 v[244:247], v187 offset:7168
	global_load_lds_dwordx4 v164, s[22:23]
	s_add_i32 m0, s29, 0xe000
	s_nop 0
	global_load_lds_dwordx4 v166, s[22:23]
	s_waitcnt vmcnt(8) lgkmcnt(0)
	s_barrier
	v_mfma_f32_16x16x32_bf16 v[128:131], v[132:135], v[176:179], v[128:131]
	v_mfma_f32_16x16x32_bf16 v[124:127], v[140:143], v[176:179], v[124:127]
	v_mfma_f32_16x16x32_bf16 v[112:115], v[132:135], v[192:195], v[112:115]
	v_mfma_f32_16x16x32_bf16 v[108:111], v[140:143], v[192:195], v[108:111]
	v_mfma_f32_16x16x32_bf16 v[96:99], v[132:135], v[232:235], v[96:99]
	v_mfma_f32_16x16x32_bf16 v[92:95], v[140:143], v[232:235], v[92:95]
	v_mfma_f32_16x16x32_bf16 v[80:83], v[132:135], v[240:243], v[80:83]
	v_mfma_f32_16x16x32_bf16 v[76:79], v[140:143], v[240:243], v[76:79]
	v_mfma_f32_16x16x32_bf16 v[128:131], v[136:139], v[180:183], v[128:131]
	v_mfma_f32_16x16x32_bf16 v[124:127], v[144:147], v[180:183], v[124:127]
	v_mfma_f32_16x16x32_bf16 v[112:115], v[136:139], v[210:213], v[112:115]
	v_mfma_f32_16x16x32_bf16 v[108:111], v[144:147], v[210:213], v[108:111]
	v_mfma_f32_16x16x32_bf16 v[96:99], v[136:139], v[236:239], v[96:99]
	v_mfma_f32_16x16x32_bf16 v[92:95], v[144:147], v[236:239], v[92:95]
	v_mfma_f32_16x16x32_bf16 v[80:83], v[136:139], v[244:247], v[80:83]
	v_mfma_f32_16x16x32_bf16 v[76:79], v[144:147], v[244:247], v[76:79]
	v_mfma_f32_16x16x32_bf16 v[120:123], v[148:151], v[176:179], v[120:123]
	v_mfma_f32_16x16x32_bf16 v[116:119], v[168:171], v[176:179], v[116:119]
	v_mfma_f32_16x16x32_bf16 v[104:107], v[148:151], v[192:195], v[104:107]
	v_mfma_f32_16x16x32_bf16 v[100:103], v[168:171], v[192:195], v[100:103]
	v_mfma_f32_16x16x32_bf16 v[88:91], v[148:151], v[232:235], v[88:91]
	v_mfma_f32_16x16x32_bf16 v[84:87], v[168:171], v[232:235], v[84:87]
	v_mfma_f32_16x16x32_bf16 v[72:75], v[148:151], v[240:243], v[72:75]
	v_mfma_f32_16x16x32_bf16 v[68:71], v[168:171], v[240:243], v[68:71]
	v_mfma_f32_16x16x32_bf16 v[120:123], v[152:155], v[180:183], v[120:123]
	v_mfma_f32_16x16x32_bf16 v[116:119], v[172:175], v[180:183], v[116:119]
	v_mfma_f32_16x16x32_bf16 v[104:107], v[152:155], v[210:213], v[104:107]
	v_mfma_f32_16x16x32_bf16 v[100:103], v[172:175], v[210:213], v[100:103]
	v_mfma_f32_16x16x32_bf16 v[88:91], v[152:155], v[236:239], v[88:91]
	v_mfma_f32_16x16x32_bf16 v[84:87], v[172:175], v[236:239], v[84:87]
	v_mfma_f32_16x16x32_bf16 v[72:75], v[152:155], v[244:247], v[72:75]
	v_mfma_f32_16x16x32_bf16 v[68:71], v[172:175], v[244:247], v[68:71]
	s_barrier
	s_add_i32 s22, s34, s0
	s_mov_b32 m0, s22
	ds_read_b128 v[176:179], v187 offset:16384
	ds_read_b128 v[180:183], v187 offset:17408
	ds_read_b128 v[192:195], v187 offset:18432
	ds_read_b128 v[210:213], v187 offset:19456
	ds_read_b128 v[232:235], v187 offset:20480
	ds_read_b128 v[236:239], v187 offset:21504
	ds_read_b128 v[240:243], v187 offset:22528
	ds_read_b128 v[244:247], v187 offset:23552
	global_load_lds_dwordx4 v156, s[48:49]
	s_add_i32 m0, s22, 0x2000
	s_add_u32 s22, s48, 0x4000
	s_addc_u32 s23, s49, 0
	s_add_i32 s34, s35, s0
	global_load_lds_dwordx4 v160, s[48:49]
	s_mov_b32 m0, s34
	s_nop 0
	global_load_lds_dwordx4 v156, s[22:23]
	s_add_i32 m0, s34, 0x2000
	s_nop 0
	global_load_lds_dwordx4 v160, s[22:23]
	s_mov_b32 m0, s29
	s_nop 0
	global_load_lds_dwordx4 v158, s[50:51]
	s_waitcnt vmcnt(7) lgkmcnt(0)
	s_barrier
	v_mfma_f32_16x16x32_bf16 v[64:67], v[132:135], v[176:179], v[64:67]
	v_mfma_f32_16x16x32_bf16 v[60:63], v[140:143], v[176:179], v[60:63]
	v_mfma_f32_16x16x32_bf16 v[48:51], v[132:135], v[192:195], v[48:51]
	v_mfma_f32_16x16x32_bf16 v[44:47], v[140:143], v[192:195], v[44:47]
	v_mfma_f32_16x16x32_bf16 v[30:33], v[132:135], v[232:235], v[30:33]
	v_mfma_f32_16x16x32_bf16 v[26:29], v[140:143], v[232:235], v[26:29]
	v_mfma_f32_16x16x32_bf16 v[14:17], v[132:135], v[240:243], v[14:17]
	v_mfma_f32_16x16x32_bf16 v[10:13], v[140:143], v[240:243], v[10:13]
	v_mfma_f32_16x16x32_bf16 v[64:67], v[136:139], v[180:183], v[64:67]
	v_mfma_f32_16x16x32_bf16 v[60:63], v[144:147], v[180:183], v[60:63]
	v_mfma_f32_16x16x32_bf16 v[48:51], v[136:139], v[210:213], v[48:51]
	v_mfma_f32_16x16x32_bf16 v[44:47], v[144:147], v[210:213], v[44:47]
	v_mfma_f32_16x16x32_bf16 v[30:33], v[136:139], v[236:239], v[30:33]
	v_mfma_f32_16x16x32_bf16 v[26:29], v[144:147], v[236:239], v[26:29]
	v_mfma_f32_16x16x32_bf16 v[14:17], v[136:139], v[244:247], v[14:17]
	v_mfma_f32_16x16x32_bf16 v[10:13], v[144:147], v[244:247], v[10:13]
	v_mfma_f32_16x16x32_bf16 v[56:59], v[148:151], v[176:179], v[56:59]
	v_mfma_f32_16x16x32_bf16 v[52:55], v[168:171], v[176:179], v[52:55]
	v_mfma_f32_16x16x32_bf16 v[40:43], v[148:151], v[192:195], v[40:43]
	v_mfma_f32_16x16x32_bf16 v[36:39], v[168:171], v[192:195], v[36:39]
	v_mfma_f32_16x16x32_bf16 v[22:25], v[148:151], v[232:235], v[22:25]
	v_mfma_f32_16x16x32_bf16 v[18:21], v[168:171], v[232:235], v[18:21]
	v_mfma_f32_16x16x32_bf16 v[6:9], v[148:151], v[240:243], v[6:9]
	v_mfma_f32_16x16x32_bf16 v[2:5], v[168:171], v[240:243], v[2:5]
	v_mfma_f32_16x16x32_bf16 v[56:59], v[152:155], v[180:183], v[56:59]
	v_mfma_f32_16x16x32_bf16 v[52:55], v[172:175], v[180:183], v[52:55]
	v_mfma_f32_16x16x32_bf16 v[40:43], v[152:155], v[210:213], v[40:43]
	v_mfma_f32_16x16x32_bf16 v[36:39], v[172:175], v[210:213], v[36:39]
	v_mfma_f32_16x16x32_bf16 v[22:25], v[152:155], v[236:239], v[22:25]
	v_mfma_f32_16x16x32_bf16 v[18:21], v[172:175], v[236:239], v[18:21]
	v_mfma_f32_16x16x32_bf16 v[6:9], v[152:155], v[244:247], v[6:9]
	v_mfma_f32_16x16x32_bf16 v[2:5], v[172:175], v[244:247], v[2:5]
	s_barrier
	s_mov_b32 m0, s45
	s_nop 0
	global_load_lds_dwordx4 v162, s[50:51]
	s_add_i32 s34, 0, 0x18000
	s_add_i32 s35, 0, 0x1c000
	ds_read_b128 v[132:135], v188 offset:32768
	ds_read_b128 v[136:139], v188 offset:33792
	ds_read_b128 v[140:143], v188 offset:34816
	ds_read_b128 v[144:147], v188 offset:35840
	ds_read_b128 v[148:151], v188 offset:49152
	ds_read_b128 v[152:155], v188 offset:50176
	ds_read_b128 v[168:171], v188 offset:51200
	ds_read_b128 v[172:175], v188 offset:52224
	s_add_u32 s22, s50, 0x2b0000
	s_addc_u32 s23, s51, 0
	s_mov_b32 m0, s82
	ds_read_b128 v[176:179], v187 offset:32768
	ds_read_b128 v[180:183], v187 offset:33792
	ds_read_b128 v[192:195], v187 offset:34816
	ds_read_b128 v[210:213], v187 offset:35840
	ds_read_b128 v[232:235], v187 offset:36864
	ds_read_b128 v[236:239], v187 offset:37888
	ds_read_b128 v[240:243], v187 offset:38912
	ds_read_b128 v[244:247], v187 offset:39936
	global_load_lds_dwordx4 v158, s[22:23]
	s_mov_b32 m0, s90
	s_nop 0
	global_load_lds_dwordx4 v162, s[22:23]
	s_waitcnt vmcnt(8) lgkmcnt(0)
	s_barrier
	v_mfma_f32_16x16x32_bf16 v[128:131], v[132:135], v[176:179], v[128:131]
	v_mfma_f32_16x16x32_bf16 v[124:127], v[140:143], v[176:179], v[124:127]
	v_mfma_f32_16x16x32_bf16 v[112:115], v[132:135], v[192:195], v[112:115]
	v_mfma_f32_16x16x32_bf16 v[108:111], v[140:143], v[192:195], v[108:111]
	v_mfma_f32_16x16x32_bf16 v[96:99], v[132:135], v[232:235], v[96:99]
	v_mfma_f32_16x16x32_bf16 v[92:95], v[140:143], v[232:235], v[92:95]
	v_mfma_f32_16x16x32_bf16 v[80:83], v[132:135], v[240:243], v[80:83]
	v_mfma_f32_16x16x32_bf16 v[76:79], v[140:143], v[240:243], v[76:79]
	v_mfma_f32_16x16x32_bf16 v[128:131], v[136:139], v[180:183], v[128:131]
	v_mfma_f32_16x16x32_bf16 v[124:127], v[144:147], v[180:183], v[124:127]
	v_mfma_f32_16x16x32_bf16 v[112:115], v[136:139], v[210:213], v[112:115]
	v_mfma_f32_16x16x32_bf16 v[108:111], v[144:147], v[210:213], v[108:111]
	v_mfma_f32_16x16x32_bf16 v[96:99], v[136:139], v[236:239], v[96:99]
	v_mfma_f32_16x16x32_bf16 v[92:95], v[144:147], v[236:239], v[92:95]
	v_mfma_f32_16x16x32_bf16 v[80:83], v[136:139], v[244:247], v[80:83]
	v_mfma_f32_16x16x32_bf16 v[76:79], v[144:147], v[244:247], v[76:79]
	v_mfma_f32_16x16x32_bf16 v[120:123], v[148:151], v[176:179], v[120:123]
	v_mfma_f32_16x16x32_bf16 v[116:119], v[168:171], v[176:179], v[116:119]
	v_mfma_f32_16x16x32_bf16 v[104:107], v[148:151], v[192:195], v[104:107]
	v_mfma_f32_16x16x32_bf16 v[100:103], v[168:171], v[192:195], v[100:103]
	v_mfma_f32_16x16x32_bf16 v[88:91], v[148:151], v[232:235], v[88:91]
	v_mfma_f32_16x16x32_bf16 v[84:87], v[168:171], v[232:235], v[84:87]
	v_mfma_f32_16x16x32_bf16 v[72:75], v[148:151], v[240:243], v[72:75]
	v_mfma_f32_16x16x32_bf16 v[68:71], v[168:171], v[240:243], v[68:71]
	v_mfma_f32_16x16x32_bf16 v[120:123], v[152:155], v[180:183], v[120:123]
	v_mfma_f32_16x16x32_bf16 v[116:119], v[172:175], v[180:183], v[116:119]
	v_mfma_f32_16x16x32_bf16 v[104:107], v[152:155], v[210:213], v[104:107]
	v_mfma_f32_16x16x32_bf16 v[100:103], v[172:175], v[210:213], v[100:103]
	v_mfma_f32_16x16x32_bf16 v[88:91], v[152:155], v[236:239], v[88:91]
	v_mfma_f32_16x16x32_bf16 v[84:87], v[172:175], v[236:239], v[84:87]
	v_mfma_f32_16x16x32_bf16 v[72:75], v[152:155], v[244:247], v[72:75]
	v_mfma_f32_16x16x32_bf16 v[68:71], v[172:175], v[244:247], v[68:71]
	s_barrier
	s_add_u32 s22, s48, 0x8000
	s_addc_u32 s23, s49, 0
	s_add_i32 s34, s34, s0
	s_mov_b32 m0, s34
	ds_read_b128 v[176:179], v187 offset:49152
	ds_read_b128 v[180:183], v187 offset:50176
	ds_read_b128 v[192:195], v187 offset:51200
	ds_read_b128 v[210:213], v187 offset:52224
	ds_read_b128 v[232:235], v187 offset:53248
	ds_read_b128 v[236:239], v187 offset:54272
	ds_read_b128 v[240:243], v187 offset:55296
	ds_read_b128 v[244:247], v187 offset:56320
	global_load_lds_dwordx4 v156, s[22:23]
	s_add_i32 m0, s34, 0x2000
	s_mov_b64 s[100:101], s[22:23]
	s_add_u32 s22, s48, 0xc000
	s_addc_u32 s23, s49, 0
	s_add_i32 s34, s35, s0
	global_load_lds_dwordx4 v160, s[100:101]
	s_mov_b32 m0, s34
	s_nop 0
	global_load_lds_dwordx4 v156, s[22:23]
	s_add_i32 m0, s34, 0x2000
	s_nop 0
	global_load_lds_dwordx4 v160, s[22:23]
	s_mov_b32 m0, s91
	s_nop 0
	s_add_u32 s100, s50, s92
	s_addc_u32 s101, s51, s93
	global_load_lds_dwordx4 v158, s[100:101]
	s_mov_b32 m0, s30
	s_nop 0
	s_add_u32 s100, s50, s92
	s_addc_u32 s101, s51, s93
	global_load_lds_dwordx4 v162, s[100:101]
	s_waitcnt vmcnt(8) lgkmcnt(0)
	s_barrier
	v_mfma_f32_16x16x32_bf16 v[64:67], v[132:135], v[176:179], v[64:67]
	v_mfma_f32_16x16x32_bf16 v[60:63], v[140:143], v[176:179], v[60:63]
	v_mfma_f32_16x16x32_bf16 v[48:51], v[132:135], v[192:195], v[48:51]
	v_mfma_f32_16x16x32_bf16 v[44:47], v[140:143], v[192:195], v[44:47]
	v_mfma_f32_16x16x32_bf16 v[30:33], v[132:135], v[232:235], v[30:33]
	v_mfma_f32_16x16x32_bf16 v[26:29], v[140:143], v[232:235], v[26:29]
	v_mfma_f32_16x16x32_bf16 v[14:17], v[132:135], v[240:243], v[14:17]
	v_mfma_f32_16x16x32_bf16 v[10:13], v[140:143], v[240:243], v[10:13]
	v_mfma_f32_16x16x32_bf16 v[64:67], v[136:139], v[180:183], v[64:67]
	v_mfma_f32_16x16x32_bf16 v[60:63], v[144:147], v[180:183], v[60:63]
	v_mfma_f32_16x16x32_bf16 v[48:51], v[136:139], v[210:213], v[48:51]
	v_mfma_f32_16x16x32_bf16 v[44:47], v[144:147], v[210:213], v[44:47]
	v_mfma_f32_16x16x32_bf16 v[30:33], v[136:139], v[236:239], v[30:33]
	v_mfma_f32_16x16x32_bf16 v[26:29], v[144:147], v[236:239], v[26:29]
	v_mfma_f32_16x16x32_bf16 v[14:17], v[136:139], v[244:247], v[14:17]
	v_mfma_f32_16x16x32_bf16 v[10:13], v[144:147], v[244:247], v[10:13]
	v_mfma_f32_16x16x32_bf16 v[56:59], v[148:151], v[176:179], v[56:59]
	v_mfma_f32_16x16x32_bf16 v[52:55], v[168:171], v[176:179], v[52:55]
	v_mfma_f32_16x16x32_bf16 v[40:43], v[148:151], v[192:195], v[40:43]
	v_mfma_f32_16x16x32_bf16 v[36:39], v[168:171], v[192:195], v[36:39]
	v_mfma_f32_16x16x32_bf16 v[22:25], v[148:151], v[232:235], v[22:25]
	v_mfma_f32_16x16x32_bf16 v[18:21], v[168:171], v[232:235], v[18:21]
	v_mfma_f32_16x16x32_bf16 v[6:9], v[148:151], v[240:243], v[6:9]
	v_mfma_f32_16x16x32_bf16 v[2:5], v[168:171], v[240:243], v[2:5]
	v_mfma_f32_16x16x32_bf16 v[56:59], v[152:155], v[180:183], v[56:59]
	v_mfma_f32_16x16x32_bf16 v[52:55], v[172:175], v[180:183], v[52:55]
	v_mfma_f32_16x16x32_bf16 v[40:43], v[152:155], v[210:213], v[40:43]
	v_mfma_f32_16x16x32_bf16 v[36:39], v[172:175], v[210:213], v[36:39]
	v_mfma_f32_16x16x32_bf16 v[22:25], v[152:155], v[236:239], v[22:25]
	v_mfma_f32_16x16x32_bf16 v[18:21], v[172:175], v[236:239], v[18:21]
	v_mfma_f32_16x16x32_bf16 v[6:9], v[152:155], v[244:247], v[6:9]
	v_mfma_f32_16x16x32_bf16 v[2:5], v[172:175], v[244:247], v[2:5]
	s_barrier
	s_add_i32 s60, s60, 2
	s_add_u32 s58, s58, 0x10000
	s_addc_u32 s59, s59, 0
	s_cmpk_gt_u32 s60, 0xa9
	s_mov_b64 s[22:23], s[42:43]
	s_cbranch_scc0 .LBB0_1261
	s_and_b64 vcc, exec, s[46:47]
	s_cbranch_vccz .LBB0_1264
	s_barrier
